# RMSNorm phases: hand-written fast path for the 8 prompt rows of each wave, 4 rows of loads in flight
# baseline (speedup 1.0000x reference)
; #define GAS __attribute__((address_space(1)))
; __device__ __forceinline__ void phase_norm(Frame& F, int l, int mode) {
;     ...
;     const bool from_in = (mode == 0 && l == 0);
;     const GAS bf16* XR = (mode == 2) ? XS : XB;
;     GAS bf16* XW = (mode == 1 && l == NL - 1) ? XS : XB;
;     f32x4 nf[4][2]; v4u nb[4];
;     ...
;     if (gw < M) NORM_LOAD(gw);
;     for (int m = gw; m < M; m += NGW) {
;     ...
;         if (mode == 0) {
;             float* so = nullptr;
;             if (m < MP) { if ((m & (TP - 1)) == TP - 1) so = out_ + O_SHIFTP + ((size_t)l * BP + (m >> 12)) * D; }
;             else { const int ms = m - MP; if ((ms & (TS - 1)) == TS - 1) so = out_ + O_SHIFTS + ((size_t)l * BS + (ms >> 6)) * D; }
;             if (so) {
.LBB0_181:
	s_cmp_eq_u32 s91, 0
	s_cbranch_scc1 .Lnf_norm1_done
	s_cmpk_eq_i32 s8, 0x7ff
	s_cbranch_scc1 .Lnf_norm1_done
	s_movk_i32 s64, 0x28
	s_mov_b32 s65, 0
	s_mov_b32 s72, s8
	s_branch .Lnf_shared
.Lnf_ret_norm1:
	s_add_i32 s8, s8, 0x4000

; #define GAS __attribute__((address_space(1)))
; __device__ __forceinline__ void unpack8(const v4u w, float (&f)[8]) { f[0] = bf_lo(w.x); f[1] = bf_hi(w.x); f[2] = bf_lo(w.y); f[3] = bf_hi(w.y); f[4] = bf_lo(w.z); f[5] = bf_hi(w.z); f[6] = bf_lo(w.w); f[7] = bf_hi(w.w); }
; __device__ __forceinline__ void phase_norm(Frame& F, int l, int mode) {
;     ...
;     f32x4 g[4][2];
; #pragma unroll
;     for (int q = 0; q < 4; ++q) { const GAS f32x4* gp = (const GAS f32x4*)(gain + q * 512 + lane * 8); g[q][0] = gp[0]; g[q][1] = gp[1]; }
;     const bool from_in = (mode == 0 && l == 0);
;     const GAS bf16* XR = (mode == 2) ? XS : XB;
;     GAS bf16* XW = (mode == 1 && l == NL - 1) ? XS : XB;
;     f32x4 nf[4][2]; v4u nb[4];
;     ...
;     if (gw < M) NORM_LOAD(gw);
;     for (int m = gw; m < M; m += NGW) {
;         float v[4][8];
;         if (from_in) {
; #pragma unroll
;             for (int q = 0; q < 4; ++q) { v[q][0] = nf[q][0].x; v[q][1] = nf[q][0].y; v[q][2] = nf[q][0].z; v[q][3] = nf[q][0].w; v[q][4] = nf[q][1].x; v[q][5] = nf[q][1].y; v[q][6] = nf[q][1].z; v[q][7] = nf[q][1].w; } }
;         else {
; #pragma unroll
;             for (int q = 0; q < 4; ++q) unpack8(nb[q], v[q]); }
;         if (m + NGW < M) NORM_LOAD(m + NGW);
.LBB0_1083:
	s_andn2_b64 vcc, exec, s[8:9]
	s_cbranch_vccnz .LBB0_1141
	v_readlane_b32 s0, v254, 0
	v_readlane_b32 s1, v254, 1
	s_mov_b32 s16, s91
	s_mov_b64 s[18:19], s[0:1]
	s_waitcnt lgkmcnt(0)
	s_load_dwordx4 s[8:11], s[0:1], 0xd0
	v_readlane_b32 s14, v254, 12
	v_mbcnt_lo_u32_b32 v0, -1, 0
	v_mbcnt_hi_u32_b32 v0, -1, v0
	s_waitcnt lgkmcnt(0)
	s_movk_i32 s64, 0xb0
	s_mov_b32 s65, 1
	s_mov_b32 s72, s14
.Lnf_shared:
	v_readlane_b32 s20, v254, 0
	v_readlane_b32 s21, v254, 1
	s_nop 3
	s_load_dwordx2 s[22:23], s[20:21], s64
	s_load_dwordx4 s[28:31], s[20:21], 0xd0
	v_mbcnt_lo_u32_b32 v208, -1, 0
	v_mbcnt_hi_u32_b32 v208, -1, v208
	v_lshlrev_b32_e32 v209, 4, v208
	v_lshlrev_b32_e32 v210, 5, v208
	v_mov_b32_e32 v216, 0x358637bd
	s_waitcnt lgkmcnt(0)
	s_lshl_b32 s24, s91, 13
	s_add_u32 s22, s22, s24
	s_addc_u32 s23, s23, 0
	s_add_u32 s52, s22, 0x1000
	s_addc_u32 s53, s23, 0
	s_lshl_b32 s24, s72, 12
	s_add_u32 s34, s28, s24
	s_addc_u32 s35, s29, 0
	s_add_u32 s36, s30, s24
	s_addc_u32 s37, s31, 0
	s_add_u32 s36, s36, 0x1eb00000
	s_addc_u32 s37, s37, 0
	global_load_dwordx4 v[82:85], v210, s[22:23] offset:0
	global_load_dwordx4 v[86:89], v210, s[22:23] offset:16
	global_load_dwordx4 v[90:93], v210, s[22:23] offset:2048
	global_load_dwordx4 v[94:97], v210, s[22:23] offset:2064
	global_load_dwordx4 v[98:101], v210, s[52:53] offset:0
	global_load_dwordx4 v[102:105], v210, s[52:53] offset:16
	global_load_dwordx4 v[106:109], v210, s[52:53] offset:2048
	global_load_dwordx4 v[110:113], v210, s[52:53] offset:2064
	global_load_dwordx4 v[114:117], v209, s[34:35] offset:0
	global_load_dwordx4 v[118:121], v209, s[34:35] offset:1024
	global_load_dwordx4 v[122:125], v209, s[34:35] offset:2048
	global_load_dwordx4 v[126:129], v209, s[34:35] offset:3072
	s_add_u32 s34, s34, 0x800000
	s_addc_u32 s35, s35, 0
	global_load_dwordx4 v[130:133], v209, s[34:35] offset:0
	global_load_dwordx4 v[134:137], v209, s[34:35] offset:1024
	global_load_dwordx4 v[138:141], v209, s[34:35] offset:2048
	global_load_dwordx4 v[142:145], v209, s[34:35] offset:3072
	s_add_u32 s34, s34, 0x800000
	s_addc_u32 s35, s35, 0
	global_load_dwordx4 v[146:149], v209, s[34:35] offset:0
	global_load_dwordx4 v[150:153], v209, s[34:35] offset:1024
	global_load_dwordx4 v[154:157], v209, s[34:35] offset:2048
	global_load_dwordx4 v[158:161], v209, s[34:35] offset:3072
	s_add_u32 s34, s34, 0x800000
	s_addc_u32 s35, s35, 0
	global_load_dwordx4 v[162:165], v209, s[34:35] offset:0
	global_load_dwordx4 v[166:169], v209, s[34:35] offset:1024
	global_load_dwordx4 v[170:173], v209, s[34:35] offset:2048
	global_load_dwordx4 v[174:177], v209, s[34:35] offset:3072
	s_add_u32 s34, s34, 0x800000
	s_addc_u32 s35, s35, 0
	s_mov_b32 s73, 0
.Lnf_pass:
	s_cmp_eq_u32 s73, 0
	s_cbranch_scc0 .Lnf_w1_0
	s_waitcnt vmcnt(12)
	s_branch .Lnf_go_0
.Lnf_w1_0:
	s_waitcnt vmcnt(28)
.Lnf_go_0:
	v_lshlrev_b32_e32 v4, 16, v114
	v_and_b32_e32 v5, 0xffff0000, v114
	v_lshlrev_b32_e32 v6, 16, v115
	v_and_b32_e32 v7, 0xffff0000, v115
	v_lshlrev_b32_e32 v8, 16, v116
	v_and_b32_e32 v9, 0xffff0000, v116
	v_lshlrev_b32_e32 v10, 16, v117
	v_and_b32_e32 v11, 0xffff0000, v117
	v_lshlrev_b32_e32 v12, 16, v118
	v_and_b32_e32 v13, 0xffff0000, v118
	v_lshlrev_b32_e32 v14, 16, v119
	v_and_b32_e32 v15, 0xffff0000, v119
	v_lshlrev_b32_e32 v16, 16, v120
	v_and_b32_e32 v17, 0xffff0000, v120
	v_lshlrev_b32_e32 v18, 16, v121
	v_and_b32_e32 v19, 0xffff0000, v121
	v_lshlrev_b32_e32 v20, 16, v122
	v_and_b32_e32 v21, 0xffff0000, v122
	v_lshlrev_b32_e32 v22, 16, v123
	v_and_b32_e32 v23, 0xffff0000, v123
	v_lshlrev_b32_e32 v24, 16, v124
	v_and_b32_e32 v25, 0xffff0000, v124
	v_lshlrev_b32_e32 v26, 16, v125
	v_and_b32_e32 v27, 0xffff0000, v125
	v_lshlrev_b32_e32 v28, 16, v126
	v_and_b32_e32 v29, 0xffff0000, v126
	v_lshlrev_b32_e32 v30, 16, v127
	v_and_b32_e32 v31, 0xffff0000, v127
	v_lshlrev_b32_e32 v32, 16, v128
	v_and_b32_e32 v33, 0xffff0000, v128
	v_lshlrev_b32_e32 v34, 16, v129
	v_and_b32_e32 v35, 0xffff0000, v129
	s_cmp_eq_u32 s73, 0
	s_cbranch_scc0 .Lnf_nl_0
	global_load_dwordx4 v[114:117], v209, s[34:35] offset:0
	global_load_dwordx4 v[118:121], v209, s[34:35] offset:1024
	global_load_dwordx4 v[122:125], v209, s[34:35] offset:2048
	global_load_dwordx4 v[126:129], v209, s[34:35] offset:3072
	s_add_u32 s34, s34, 0x800000
	s_addc_u32 s35, s35, 0
; #define GAS __attribute__((address_space(1)))
; __device__ __forceinline__ void unpack8(const v4u w, float (&f)[8]) { f[0] = bf_lo(w.x); f[1] = bf_hi(w.x); f[2] = bf_lo(w.y); f[3] = bf_hi(w.y); f[4] = bf_lo(w.z); f[5] = bf_hi(w.z); f[6] = bf_lo(w.w); f[7] = bf_hi(w.w); }
; __device__ __forceinline__ v4u pack8(const float (&f)[8]) { v4u o; o.x = pk2(f[0], f[1]); o.y = pk2(f[2], f[3]); o.z = pk2(f[4], f[5]); o.w = pk2(f[6], f[7]); return o; }
; __device__ __forceinline__ void phase_norm(Frame& F, int l, int mode) {
;     ...
;         else {
; #pragma unroll
;             for (int q = 0; q < 4; ++q) unpack8(nb[q], v[q]); }
;         if (m + NGW < M) NORM_LOAD(m + NGW);
;     ...
;         float s = 0.f;
; #pragma unroll
;         for (int q = 0; q < 4; ++q)
; #pragma unroll
;             for (int j = 0; j < 8; ++j) s += v[q][j] * v[q][j];
;         const float rstd = __builtin_amdgcn_rsqf(wave_sum(s) * (1.f / D) + RMS_EPS);
; #pragma unroll
;         for (int q = 0; q < 4; ++q) { v[q][0] *= rstd * g[q][0].x; v[q][1] *= rstd * g[q][0].y; v[q][2] *= rstd * g[q][0].z; v[q][3] *= rstd * g[q][0].w; v[q][4] *= rstd * g[q][1].x; v[q][5] *= rstd * g[q][1].y; v[q][6] *= rstd * g[q][1].z; v[q][7] *= rstd * g[q][1].w; }
;         if (mode == 2) {
; #pragma unroll
;             for (int q = 0; q < 4; ++q) { GAS f32x4* o = (GAS f32x4*)(out_ + (size_t)m * D + q * 512 + lane * 8); o[0] = (f32x4){v[q][0], v[q][1], v[q][2], v[q][3]}; o[1] = (f32x4){v[q][4], v[q][5], v[q][6], v[q][7]}; }
;             continue; }
; #pragma unroll
;         for (int q = 0; q < 4; ++q) *(GAS v4u*)(HB + (size_t)m * D + q * 512 + lane * 8) = pack8(v[q]);
.Lnf_nl_0:
	v_pk_mul_f32 v[218:219], v[4:5], v[4:5]
	v_pk_fma_f32 v[218:219], v[6:7], v[6:7], v[218:219]
	v_pk_fma_f32 v[218:219], v[8:9], v[8:9], v[218:219]
	v_pk_fma_f32 v[218:219], v[10:11], v[10:11], v[218:219]
	v_pk_fma_f32 v[218:219], v[12:13], v[12:13], v[218:219]
	v_pk_fma_f32 v[218:219], v[14:15], v[14:15], v[218:219]
	v_pk_fma_f32 v[218:219], v[16:17], v[16:17], v[218:219]
	v_pk_fma_f32 v[218:219], v[18:19], v[18:19], v[218:219]
	v_pk_fma_f32 v[218:219], v[20:21], v[20:21], v[218:219]
	v_pk_fma_f32 v[218:219], v[22:23], v[22:23], v[218:219]
	v_pk_fma_f32 v[218:219], v[24:25], v[24:25], v[218:219]
	v_pk_fma_f32 v[218:219], v[26:27], v[26:27], v[218:219]
	v_pk_fma_f32 v[218:219], v[28:29], v[28:29], v[218:219]
	v_pk_fma_f32 v[218:219], v[30:31], v[30:31], v[218:219]
	v_pk_fma_f32 v[218:219], v[32:33], v[32:33], v[218:219]
	v_pk_fma_f32 v[218:219], v[34:35], v[34:35], v[218:219]
	v_add_f32_e32 v211, v218, v219
	s_nop 1
	v_add_f32_dpp v211, v211, v211 quad_perm:[1,0,3,2] row_mask:0xf bank_mask:0xf bound_ctrl:1
	s_nop 1
	v_add_f32_dpp v211, v211, v211 quad_perm:[2,3,0,1] row_mask:0xf bank_mask:0xf bound_ctrl:1
	s_nop 1
	v_add_f32_dpp v211, v211, v211 row_half_mirror row_mask:0xf bank_mask:0xf bound_ctrl:1
	s_nop 1
	v_add_f32_dpp v211, v211, v211 row_mirror row_mask:0xf bank_mask:0xf bound_ctrl:1
	s_nop 1
	v_readlane_b32 s24, v211, 0
	v_readlane_b32 s25, v211, 16
	v_readlane_b32 s62, v211, 32
	v_readlane_b32 s63, v211, 48
	s_nop 1
	v_mov_b32_e32 v212, s25
	v_mov_b32_e32 v214, s63
	v_add_f32_e32 v212, s24, v212
	v_add_f32_e32 v214, s62, v214
	v_add_f32_e32 v212, v212, v214
	v_fmamk_f32 v212, v212, 0x3a000000, v216
	v_rsq_f32_e32 v212, v212
	s_nop 0
	v_pk_mul_f32 v[36:37], v[82:83], v[212:213] op_sel_hi:[1,0]
	v_pk_mul_f32 v[38:39], v[84:85], v[212:213] op_sel_hi:[1,0]
	v_pk_mul_f32 v[40:41], v[86:87], v[212:213] op_sel_hi:[1,0]
	v_pk_mul_f32 v[42:43], v[88:89], v[212:213] op_sel_hi:[1,0]
	v_pk_mul_f32 v[44:45], v[90:91], v[212:213] op_sel_hi:[1,0]
	v_pk_mul_f32 v[46:47], v[92:93], v[212:213] op_sel_hi:[1,0]
	v_pk_mul_f32 v[48:49], v[94:95], v[212:213] op_sel_hi:[1,0]
	v_pk_mul_f32 v[50:51], v[96:97], v[212:213] op_sel_hi:[1,0]
	v_pk_mul_f32 v[52:53], v[98:99], v[212:213] op_sel_hi:[1,0]
	v_pk_mul_f32 v[54:55], v[100:101], v[212:213] op_sel_hi:[1,0]
	v_pk_mul_f32 v[56:57], v[102:103], v[212:213] op_sel_hi:[1,0]
	v_pk_mul_f32 v[58:59], v[104:105], v[212:213] op_sel_hi:[1,0]
	v_pk_mul_f32 v[60:61], v[106:107], v[212:213] op_sel_hi:[1,0]
	v_pk_mul_f32 v[62:63], v[108:109], v[212:213] op_sel_hi:[1,0]
	v_pk_mul_f32 v[64:65], v[110:111], v[212:213] op_sel_hi:[1,0]
	v_pk_mul_f32 v[66:67], v[112:113], v[212:213] op_sel_hi:[1,0]
	v_pk_mul_f32 v[36:37], v[4:5], v[36:37]
	v_pk_mul_f32 v[38:39], v[6:7], v[38:39]
	v_pk_mul_f32 v[40:41], v[8:9], v[40:41]
	v_pk_mul_f32 v[42:43], v[10:11], v[42:43]
	v_pk_mul_f32 v[44:45], v[12:13], v[44:45]
	v_pk_mul_f32 v[46:47], v[14:15], v[46:47]
	v_pk_mul_f32 v[48:49], v[16:17], v[48:49]
	v_pk_mul_f32 v[50:51], v[18:19], v[50:51]
	v_pk_mul_f32 v[52:53], v[20:21], v[52:53]
	v_pk_mul_f32 v[54:55], v[22:23], v[54:55]
	v_pk_mul_f32 v[56:57], v[24:25], v[56:57]
	v_pk_mul_f32 v[58:59], v[26:27], v[58:59]
	v_pk_mul_f32 v[60:61], v[28:29], v[60:61]
	v_pk_mul_f32 v[62:63], v[30:31], v[62:63]
	v_pk_mul_f32 v[64:65], v[32:33], v[64:65]
	v_pk_mul_f32 v[66:67], v[34:35], v[66:67]
	v_cvt_pk_bf16_f32 v178, v36, v37
	v_cvt_pk_bf16_f32 v179, v38, v39
	v_cvt_pk_bf16_f32 v180, v40, v41
	v_cvt_pk_bf16_f32 v181, v42, v43
	v_cvt_pk_bf16_f32 v182, v44, v45
	v_cvt_pk_bf16_f32 v183, v46, v47
	v_cvt_pk_bf16_f32 v184, v48, v49
	v_cvt_pk_bf16_f32 v185, v50, v51
	v_cvt_pk_bf16_f32 v186, v52, v53
	v_cvt_pk_bf16_f32 v187, v54, v55
	v_cvt_pk_bf16_f32 v188, v56, v57
	v_cvt_pk_bf16_f32 v189, v58, v59
	v_cvt_pk_bf16_f32 v190, v60, v61
	v_cvt_pk_bf16_f32 v191, v62, v63
	v_cvt_pk_bf16_f32 v192, v64, v65
	v_cvt_pk_bf16_f32 v193, v66, v67
	global_store_dwordx4 v209, v[178:181], s[36:37] offset:0
	global_store_dwordx4 v209, v[182:185], s[36:37] offset:1024
	global_store_dwordx4 v209, v[186:189], s[36:37] offset:2048
	global_store_dwordx4 v209, v[190:193], s[36:37] offset:3072
	s_add_u32 s36, s36, 0x800000
	s_addc_u32 s37, s37, 0
	s_cmp_eq_u32 s73, 0
	s_cbranch_scc0 .Lnf_w1_1
	s_waitcnt vmcnt(16)
	s_branch .Lnf_go_1
.Lnf_w1_1:
	s_waitcnt vmcnt(24)
.Lnf_go_1:
	v_lshlrev_b32_e32 v4, 16, v130
	v_and_b32_e32 v5, 0xffff0000, v130
	v_lshlrev_b32_e32 v6, 16, v131
	v_and_b32_e32 v7, 0xffff0000, v131
	v_lshlrev_b32_e32 v8, 16, v132
	v_and_b32_e32 v9, 0xffff0000, v132
	v_lshlrev_b32_e32 v10, 16, v133
	v_and_b32_e32 v11, 0xffff0000, v133
	v_lshlrev_b32_e32 v12, 16, v134
	v_and_b32_e32 v13, 0xffff0000, v134
	v_lshlrev_b32_e32 v14, 16, v135
	v_and_b32_e32 v15, 0xffff0000, v135
	v_lshlrev_b32_e32 v16, 16, v136
	v_and_b32_e32 v17, 0xffff0000, v136
	v_lshlrev_b32_e32 v18, 16, v137
	v_and_b32_e32 v19, 0xffff0000, v137
	v_lshlrev_b32_e32 v20, 16, v138
	v_and_b32_e32 v21, 0xffff0000, v138
	v_lshlrev_b32_e32 v22, 16, v139
	v_and_b32_e32 v23, 0xffff0000, v139
	v_lshlrev_b32_e32 v24, 16, v140
	v_and_b32_e32 v25, 0xffff0000, v140
	v_lshlrev_b32_e32 v26, 16, v141
	v_and_b32_e32 v27, 0xffff0000, v141
	v_lshlrev_b32_e32 v28, 16, v142
	v_and_b32_e32 v29, 0xffff0000, v142
	v_lshlrev_b32_e32 v30, 16, v143
	v_and_b32_e32 v31, 0xffff0000, v143
	v_lshlrev_b32_e32 v32, 16, v144
	v_and_b32_e32 v33, 0xffff0000, v144
	v_lshlrev_b32_e32 v34, 16, v145
	v_and_b32_e32 v35, 0xffff0000, v145
	s_cmp_eq_u32 s73, 0
	s_cbranch_scc0 .Lnf_nl_1
	global_load_dwordx4 v[130:133], v209, s[34:35] offset:0
	global_load_dwordx4 v[134:137], v209, s[34:35] offset:1024
	global_load_dwordx4 v[138:141], v209, s[34:35] offset:2048
	global_load_dwordx4 v[142:145], v209, s[34:35] offset:3072
	s_add_u32 s34, s34, 0x800000
	s_addc_u32 s35, s35, 0
; #define GAS __attribute__((address_space(1)))
; __device__ __forceinline__ void unpack8(const v4u w, float (&f)[8]) { f[0] = bf_lo(w.x); f[1] = bf_hi(w.x); f[2] = bf_lo(w.y); f[3] = bf_hi(w.y); f[4] = bf_lo(w.z); f[5] = bf_hi(w.z); f[6] = bf_lo(w.w); f[7] = bf_hi(w.w); }
; __device__ __forceinline__ v4u pack8(const float (&f)[8]) { v4u o; o.x = pk2(f[0], f[1]); o.y = pk2(f[2], f[3]); o.z = pk2(f[4], f[5]); o.w = pk2(f[6], f[7]); return o; }
; __device__ __forceinline__ void phase_norm(Frame& F, int l, int mode) {
;     ...
;         else {
; #pragma unroll
;             for (int q = 0; q < 4; ++q) unpack8(nb[q], v[q]); }
;         if (m + NGW < M) NORM_LOAD(m + NGW);
;     ...
;         float s = 0.f;
; #pragma unroll
;         for (int q = 0; q < 4; ++q)
; #pragma unroll
;             for (int j = 0; j < 8; ++j) s += v[q][j] * v[q][j];
;         const float rstd = __builtin_amdgcn_rsqf(wave_sum(s) * (1.f / D) + RMS_EPS);
; #pragma unroll
;         for (int q = 0; q < 4; ++q) { v[q][0] *= rstd * g[q][0].x; v[q][1] *= rstd * g[q][0].y; v[q][2] *= rstd * g[q][0].z; v[q][3] *= rstd * g[q][0].w; v[q][4] *= rstd * g[q][1].x; v[q][5] *= rstd * g[q][1].y; v[q][6] *= rstd * g[q][1].z; v[q][7] *= rstd * g[q][1].w; }
;         if (mode == 2) {
; #pragma unroll
;             for (int q = 0; q < 4; ++q) { GAS f32x4* o = (GAS f32x4*)(out_ + (size_t)m * D + q * 512 + lane * 8); o[0] = (f32x4){v[q][0], v[q][1], v[q][2], v[q][3]}; o[1] = (f32x4){v[q][4], v[q][5], v[q][6], v[q][7]}; }
;             continue; }
; #pragma unroll
;         for (int q = 0; q < 4; ++q) *(GAS v4u*)(HB + (size_t)m * D + q * 512 + lane * 8) = pack8(v[q]);
.Lnf_nl_1:
	v_pk_mul_f32 v[218:219], v[4:5], v[4:5]
	v_pk_fma_f32 v[218:219], v[6:7], v[6:7], v[218:219]
	v_pk_fma_f32 v[218:219], v[8:9], v[8:9], v[218:219]
	v_pk_fma_f32 v[218:219], v[10:11], v[10:11], v[218:219]
	v_pk_fma_f32 v[218:219], v[12:13], v[12:13], v[218:219]
	v_pk_fma_f32 v[218:219], v[14:15], v[14:15], v[218:219]
	v_pk_fma_f32 v[218:219], v[16:17], v[16:17], v[218:219]
	v_pk_fma_f32 v[218:219], v[18:19], v[18:19], v[218:219]
	v_pk_fma_f32 v[218:219], v[20:21], v[20:21], v[218:219]
	v_pk_fma_f32 v[218:219], v[22:23], v[22:23], v[218:219]
	v_pk_fma_f32 v[218:219], v[24:25], v[24:25], v[218:219]
	v_pk_fma_f32 v[218:219], v[26:27], v[26:27], v[218:219]
	v_pk_fma_f32 v[218:219], v[28:29], v[28:29], v[218:219]
	v_pk_fma_f32 v[218:219], v[30:31], v[30:31], v[218:219]
	v_pk_fma_f32 v[218:219], v[32:33], v[32:33], v[218:219]
	v_pk_fma_f32 v[218:219], v[34:35], v[34:35], v[218:219]
	v_add_f32_e32 v211, v218, v219
	s_nop 1
	v_add_f32_dpp v211, v211, v211 quad_perm:[1,0,3,2] row_mask:0xf bank_mask:0xf bound_ctrl:1
	s_nop 1
	v_add_f32_dpp v211, v211, v211 quad_perm:[2,3,0,1] row_mask:0xf bank_mask:0xf bound_ctrl:1
	s_nop 1
	v_add_f32_dpp v211, v211, v211 row_half_mirror row_mask:0xf bank_mask:0xf bound_ctrl:1
	s_nop 1
	v_add_f32_dpp v211, v211, v211 row_mirror row_mask:0xf bank_mask:0xf bound_ctrl:1
	s_nop 1
	v_readlane_b32 s24, v211, 0
	v_readlane_b32 s25, v211, 16
	v_readlane_b32 s62, v211, 32
	v_readlane_b32 s63, v211, 48
	s_nop 1
	v_mov_b32_e32 v212, s25
	v_mov_b32_e32 v214, s63
	v_add_f32_e32 v212, s24, v212
	v_add_f32_e32 v214, s62, v214
	v_add_f32_e32 v212, v212, v214
	v_fmamk_f32 v212, v212, 0x3a000000, v216
	v_rsq_f32_e32 v212, v212
	s_nop 0
	v_pk_mul_f32 v[36:37], v[82:83], v[212:213] op_sel_hi:[1,0]
	v_pk_mul_f32 v[38:39], v[84:85], v[212:213] op_sel_hi:[1,0]
	v_pk_mul_f32 v[40:41], v[86:87], v[212:213] op_sel_hi:[1,0]
	v_pk_mul_f32 v[42:43], v[88:89], v[212:213] op_sel_hi:[1,0]
	v_pk_mul_f32 v[44:45], v[90:91], v[212:213] op_sel_hi:[1,0]
	v_pk_mul_f32 v[46:47], v[92:93], v[212:213] op_sel_hi:[1,0]
	v_pk_mul_f32 v[48:49], v[94:95], v[212:213] op_sel_hi:[1,0]
	v_pk_mul_f32 v[50:51], v[96:97], v[212:213] op_sel_hi:[1,0]
	v_pk_mul_f32 v[52:53], v[98:99], v[212:213] op_sel_hi:[1,0]
	v_pk_mul_f32 v[54:55], v[100:101], v[212:213] op_sel_hi:[1,0]
	v_pk_mul_f32 v[56:57], v[102:103], v[212:213] op_sel_hi:[1,0]
	v_pk_mul_f32 v[58:59], v[104:105], v[212:213] op_sel_hi:[1,0]
	v_pk_mul_f32 v[60:61], v[106:107], v[212:213] op_sel_hi:[1,0]
	v_pk_mul_f32 v[62:63], v[108:109], v[212:213] op_sel_hi:[1,0]
	v_pk_mul_f32 v[64:65], v[110:111], v[212:213] op_sel_hi:[1,0]
	v_pk_mul_f32 v[66:67], v[112:113], v[212:213] op_sel_hi:[1,0]
	v_pk_mul_f32 v[36:37], v[4:5], v[36:37]
	v_pk_mul_f32 v[38:39], v[6:7], v[38:39]
	v_pk_mul_f32 v[40:41], v[8:9], v[40:41]
	v_pk_mul_f32 v[42:43], v[10:11], v[42:43]
	v_pk_mul_f32 v[44:45], v[12:13], v[44:45]
	v_pk_mul_f32 v[46:47], v[14:15], v[46:47]
	v_pk_mul_f32 v[48:49], v[16:17], v[48:49]
	v_pk_mul_f32 v[50:51], v[18:19], v[50:51]
	v_pk_mul_f32 v[52:53], v[20:21], v[52:53]
	v_pk_mul_f32 v[54:55], v[22:23], v[54:55]
	v_pk_mul_f32 v[56:57], v[24:25], v[56:57]
	v_pk_mul_f32 v[58:59], v[26:27], v[58:59]
	v_pk_mul_f32 v[60:61], v[28:29], v[60:61]
	v_pk_mul_f32 v[62:63], v[30:31], v[62:63]
	v_pk_mul_f32 v[64:65], v[32:33], v[64:65]
	v_pk_mul_f32 v[66:67], v[34:35], v[66:67]
	v_cvt_pk_bf16_f32 v178, v36, v37
	v_cvt_pk_bf16_f32 v179, v38, v39
	v_cvt_pk_bf16_f32 v180, v40, v41
	v_cvt_pk_bf16_f32 v181, v42, v43
	v_cvt_pk_bf16_f32 v182, v44, v45
	v_cvt_pk_bf16_f32 v183, v46, v47
	v_cvt_pk_bf16_f32 v184, v48, v49
	v_cvt_pk_bf16_f32 v185, v50, v51
	v_cvt_pk_bf16_f32 v186, v52, v53
	v_cvt_pk_bf16_f32 v187, v54, v55
	v_cvt_pk_bf16_f32 v188, v56, v57
	v_cvt_pk_bf16_f32 v189, v58, v59
	v_cvt_pk_bf16_f32 v190, v60, v61
	v_cvt_pk_bf16_f32 v191, v62, v63
	v_cvt_pk_bf16_f32 v192, v64, v65
	v_cvt_pk_bf16_f32 v193, v66, v67
	global_store_dwordx4 v209, v[178:181], s[36:37] offset:0
	global_store_dwordx4 v209, v[182:185], s[36:37] offset:1024
	global_store_dwordx4 v209, v[186:189], s[36:37] offset:2048
	global_store_dwordx4 v209, v[190:193], s[36:37] offset:3072
	s_add_u32 s36, s36, 0x800000
	s_addc_u32 s37, s37, 0
	s_cmp_eq_u32 s73, 0
	s_cbranch_scc0 .Lnf_w1_2
	s_waitcnt vmcnt(20)
	s_branch .Lnf_go_2
.Lnf_w1_2:
	s_waitcnt vmcnt(20)
.Lnf_go_2:
	v_lshlrev_b32_e32 v4, 16, v146
	v_and_b32_e32 v5, 0xffff0000, v146
	v_lshlrev_b32_e32 v6, 16, v147
	v_and_b32_e32 v7, 0xffff0000, v147
	v_lshlrev_b32_e32 v8, 16, v148
	v_and_b32_e32 v9, 0xffff0000, v148
	v_lshlrev_b32_e32 v10, 16, v149
	v_and_b32_e32 v11, 0xffff0000, v149
	v_lshlrev_b32_e32 v12, 16, v150
	v_and_b32_e32 v13, 0xffff0000, v150
	v_lshlrev_b32_e32 v14, 16, v151
	v_and_b32_e32 v15, 0xffff0000, v151
	v_lshlrev_b32_e32 v16, 16, v152
	v_and_b32_e32 v17, 0xffff0000, v152
	v_lshlrev_b32_e32 v18, 16, v153
	v_and_b32_e32 v19, 0xffff0000, v153
	v_lshlrev_b32_e32 v20, 16, v154
	v_and_b32_e32 v21, 0xffff0000, v154
	v_lshlrev_b32_e32 v22, 16, v155
	v_and_b32_e32 v23, 0xffff0000, v155
	v_lshlrev_b32_e32 v24, 16, v156
	v_and_b32_e32 v25, 0xffff0000, v156
	v_lshlrev_b32_e32 v26, 16, v157
	v_and_b32_e32 v27, 0xffff0000, v157
	v_lshlrev_b32_e32 v28, 16, v158
	v_and_b32_e32 v29, 0xffff0000, v158
	v_lshlrev_b32_e32 v30, 16, v159
	v_and_b32_e32 v31, 0xffff0000, v159
	v_lshlrev_b32_e32 v32, 16, v160
	v_and_b32_e32 v33, 0xffff0000, v160
	v_lshlrev_b32_e32 v34, 16, v161
	v_and_b32_e32 v35, 0xffff0000, v161
	s_cmp_eq_u32 s73, 0
	s_cbranch_scc0 .Lnf_nl_2
	global_load_dwordx4 v[146:149], v209, s[34:35] offset:0
	global_load_dwordx4 v[150:153], v209, s[34:35] offset:1024
	global_load_dwordx4 v[154:157], v209, s[34:35] offset:2048
	global_load_dwordx4 v[158:161], v209, s[34:35] offset:3072
	s_add_u32 s34, s34, 0x800000
	s_addc_u32 s35, s35, 0
; #define GAS __attribute__((address_space(1)))
; __device__ __forceinline__ void unpack8(const v4u w, float (&f)[8]) { f[0] = bf_lo(w.x); f[1] = bf_hi(w.x); f[2] = bf_lo(w.y); f[3] = bf_hi(w.y); f[4] = bf_lo(w.z); f[5] = bf_hi(w.z); f[6] = bf_lo(w.w); f[7] = bf_hi(w.w); }
; __device__ __forceinline__ v4u pack8(const float (&f)[8]) { v4u o; o.x = pk2(f[0], f[1]); o.y = pk2(f[2], f[3]); o.z = pk2(f[4], f[5]); o.w = pk2(f[6], f[7]); return o; }
; __device__ __forceinline__ void phase_norm(Frame& F, int l, int mode) {
;     ...
;         else {
; #pragma unroll
;             for (int q = 0; q < 4; ++q) unpack8(nb[q], v[q]); }
;         if (m + NGW < M) NORM_LOAD(m + NGW);
;     ...
;         float s = 0.f;
; #pragma unroll
;         for (int q = 0; q < 4; ++q)
; #pragma unroll
;             for (int j = 0; j < 8; ++j) s += v[q][j] * v[q][j];
;         const float rstd = __builtin_amdgcn_rsqf(wave_sum(s) * (1.f / D) + RMS_EPS);
; #pragma unroll
;         for (int q = 0; q < 4; ++q) { v[q][0] *= rstd * g[q][0].x; v[q][1] *= rstd * g[q][0].y; v[q][2] *= rstd * g[q][0].z; v[q][3] *= rstd * g[q][0].w; v[q][4] *= rstd * g[q][1].x; v[q][5] *= rstd * g[q][1].y; v[q][6] *= rstd * g[q][1].z; v[q][7] *= rstd * g[q][1].w; }
;         if (mode == 2) {
; #pragma unroll
;             for (int q = 0; q < 4; ++q) { GAS f32x4* o = (GAS f32x4*)(out_ + (size_t)m * D + q * 512 + lane * 8); o[0] = (f32x4){v[q][0], v[q][1], v[q][2], v[q][3]}; o[1] = (f32x4){v[q][4], v[q][5], v[q][6], v[q][7]}; }
;             continue; }
; #pragma unroll
;         for (int q = 0; q < 4; ++q) *(GAS v4u*)(HB + (size_t)m * D + q * 512 + lane * 8) = pack8(v[q]);
.Lnf_nl_2:
	v_pk_mul_f32 v[218:219], v[4:5], v[4:5]
	v_pk_fma_f32 v[218:219], v[6:7], v[6:7], v[218:219]
	v_pk_fma_f32 v[218:219], v[8:9], v[8:9], v[218:219]
	v_pk_fma_f32 v[218:219], v[10:11], v[10:11], v[218:219]
	v_pk_fma_f32 v[218:219], v[12:13], v[12:13], v[218:219]
	v_pk_fma_f32 v[218:219], v[14:15], v[14:15], v[218:219]
	v_pk_fma_f32 v[218:219], v[16:17], v[16:17], v[218:219]
	v_pk_fma_f32 v[218:219], v[18:19], v[18:19], v[218:219]
	v_pk_fma_f32 v[218:219], v[20:21], v[20:21], v[218:219]
	v_pk_fma_f32 v[218:219], v[22:23], v[22:23], v[218:219]
	v_pk_fma_f32 v[218:219], v[24:25], v[24:25], v[218:219]
	v_pk_fma_f32 v[218:219], v[26:27], v[26:27], v[218:219]
	v_pk_fma_f32 v[218:219], v[28:29], v[28:29], v[218:219]
	v_pk_fma_f32 v[218:219], v[30:31], v[30:31], v[218:219]
	v_pk_fma_f32 v[218:219], v[32:33], v[32:33], v[218:219]
	v_pk_fma_f32 v[218:219], v[34:35], v[34:35], v[218:219]
	v_add_f32_e32 v211, v218, v219
	s_nop 1
	v_add_f32_dpp v211, v211, v211 quad_perm:[1,0,3,2] row_mask:0xf bank_mask:0xf bound_ctrl:1
	s_nop 1
	v_add_f32_dpp v211, v211, v211 quad_perm:[2,3,0,1] row_mask:0xf bank_mask:0xf bound_ctrl:1
	s_nop 1
	v_add_f32_dpp v211, v211, v211 row_half_mirror row_mask:0xf bank_mask:0xf bound_ctrl:1
	s_nop 1
	v_add_f32_dpp v211, v211, v211 row_mirror row_mask:0xf bank_mask:0xf bound_ctrl:1
	s_nop 1
	v_readlane_b32 s24, v211, 0
	v_readlane_b32 s25, v211, 16
	v_readlane_b32 s62, v211, 32
	v_readlane_b32 s63, v211, 48
	s_nop 1
	v_mov_b32_e32 v212, s25
	v_mov_b32_e32 v214, s63
	v_add_f32_e32 v212, s24, v212
	v_add_f32_e32 v214, s62, v214
	v_add_f32_e32 v212, v212, v214
	v_fmamk_f32 v212, v212, 0x3a000000, v216
	v_rsq_f32_e32 v212, v212
	s_nop 0
	v_pk_mul_f32 v[36:37], v[82:83], v[212:213] op_sel_hi:[1,0]
	v_pk_mul_f32 v[38:39], v[84:85], v[212:213] op_sel_hi:[1,0]
	v_pk_mul_f32 v[40:41], v[86:87], v[212:213] op_sel_hi:[1,0]
	v_pk_mul_f32 v[42:43], v[88:89], v[212:213] op_sel_hi:[1,0]
	v_pk_mul_f32 v[44:45], v[90:91], v[212:213] op_sel_hi:[1,0]
	v_pk_mul_f32 v[46:47], v[92:93], v[212:213] op_sel_hi:[1,0]
	v_pk_mul_f32 v[48:49], v[94:95], v[212:213] op_sel_hi:[1,0]
	v_pk_mul_f32 v[50:51], v[96:97], v[212:213] op_sel_hi:[1,0]
	v_pk_mul_f32 v[52:53], v[98:99], v[212:213] op_sel_hi:[1,0]
	v_pk_mul_f32 v[54:55], v[100:101], v[212:213] op_sel_hi:[1,0]
	v_pk_mul_f32 v[56:57], v[102:103], v[212:213] op_sel_hi:[1,0]
	v_pk_mul_f32 v[58:59], v[104:105], v[212:213] op_sel_hi:[1,0]
	v_pk_mul_f32 v[60:61], v[106:107], v[212:213] op_sel_hi:[1,0]
	v_pk_mul_f32 v[62:63], v[108:109], v[212:213] op_sel_hi:[1,0]
	v_pk_mul_f32 v[64:65], v[110:111], v[212:213] op_sel_hi:[1,0]
	v_pk_mul_f32 v[66:67], v[112:113], v[212:213] op_sel_hi:[1,0]
	v_pk_mul_f32 v[36:37], v[4:5], v[36:37]
	v_pk_mul_f32 v[38:39], v[6:7], v[38:39]
	v_pk_mul_f32 v[40:41], v[8:9], v[40:41]
	v_pk_mul_f32 v[42:43], v[10:11], v[42:43]
	v_pk_mul_f32 v[44:45], v[12:13], v[44:45]
	v_pk_mul_f32 v[46:47], v[14:15], v[46:47]
	v_pk_mul_f32 v[48:49], v[16:17], v[48:49]
	v_pk_mul_f32 v[50:51], v[18:19], v[50:51]
	v_pk_mul_f32 v[52:53], v[20:21], v[52:53]
	v_pk_mul_f32 v[54:55], v[22:23], v[54:55]
	v_pk_mul_f32 v[56:57], v[24:25], v[56:57]
	v_pk_mul_f32 v[58:59], v[26:27], v[58:59]
	v_pk_mul_f32 v[60:61], v[28:29], v[60:61]
	v_pk_mul_f32 v[62:63], v[30:31], v[62:63]
	v_pk_mul_f32 v[64:65], v[32:33], v[64:65]
	v_pk_mul_f32 v[66:67], v[34:35], v[66:67]
	v_cvt_pk_bf16_f32 v178, v36, v37
	v_cvt_pk_bf16_f32 v179, v38, v39
	v_cvt_pk_bf16_f32 v180, v40, v41
	v_cvt_pk_bf16_f32 v181, v42, v43
	v_cvt_pk_bf16_f32 v182, v44, v45
	v_cvt_pk_bf16_f32 v183, v46, v47
	v_cvt_pk_bf16_f32 v184, v48, v49
	v_cvt_pk_bf16_f32 v185, v50, v51
	v_cvt_pk_bf16_f32 v186, v52, v53
	v_cvt_pk_bf16_f32 v187, v54, v55
	v_cvt_pk_bf16_f32 v188, v56, v57
	v_cvt_pk_bf16_f32 v189, v58, v59
	v_cvt_pk_bf16_f32 v190, v60, v61
	v_cvt_pk_bf16_f32 v191, v62, v63
	v_cvt_pk_bf16_f32 v192, v64, v65
	v_cvt_pk_bf16_f32 v193, v66, v67
	global_store_dwordx4 v209, v[178:181], s[36:37] offset:0
	global_store_dwordx4 v209, v[182:185], s[36:37] offset:1024
	global_store_dwordx4 v209, v[186:189], s[36:37] offset:2048
	global_store_dwordx4 v209, v[190:193], s[36:37] offset:3072
	s_add_u32 s36, s36, 0x800000
	s_addc_u32 s37, s37, 0
	s_cmp_eq_u32 s73, 0
	s_cbranch_scc0 .Lnf_w1_3
	s_waitcnt vmcnt(24)
	s_branch .Lnf_go_3
.Lnf_w1_3:
	s_waitcnt vmcnt(16)
.Lnf_go_3:
	v_lshlrev_b32_e32 v4, 16, v162
	v_and_b32_e32 v5, 0xffff0000, v162
	v_lshlrev_b32_e32 v6, 16, v163
	v_and_b32_e32 v7, 0xffff0000, v163
	v_lshlrev_b32_e32 v8, 16, v164
	v_and_b32_e32 v9, 0xffff0000, v164
	v_lshlrev_b32_e32 v10, 16, v165
	v_and_b32_e32 v11, 0xffff0000, v165
	v_lshlrev_b32_e32 v12, 16, v166
	v_and_b32_e32 v13, 0xffff0000, v166
	v_lshlrev_b32_e32 v14, 16, v167
	v_and_b32_e32 v15, 0xffff0000, v167
	v_lshlrev_b32_e32 v16, 16, v168
	v_and_b32_e32 v17, 0xffff0000, v168
	v_lshlrev_b32_e32 v18, 16, v169
	v_and_b32_e32 v19, 0xffff0000, v169
	v_lshlrev_b32_e32 v20, 16, v170
	v_and_b32_e32 v21, 0xffff0000, v170
	v_lshlrev_b32_e32 v22, 16, v171
	v_and_b32_e32 v23, 0xffff0000, v171
	v_lshlrev_b32_e32 v24, 16, v172
	v_and_b32_e32 v25, 0xffff0000, v172
	v_lshlrev_b32_e32 v26, 16, v173
	v_and_b32_e32 v27, 0xffff0000, v173
	v_lshlrev_b32_e32 v28, 16, v174
	v_and_b32_e32 v29, 0xffff0000, v174
	v_lshlrev_b32_e32 v30, 16, v175
	v_and_b32_e32 v31, 0xffff0000, v175
	v_lshlrev_b32_e32 v32, 16, v176
	v_and_b32_e32 v33, 0xffff0000, v176
	v_lshlrev_b32_e32 v34, 16, v177
	v_and_b32_e32 v35, 0xffff0000, v177
	s_cmp_eq_u32 s73, 0
	s_cbranch_scc0 .Lnf_nl_3
	global_load_dwordx4 v[162:165], v209, s[34:35] offset:0
	global_load_dwordx4 v[166:169], v209, s[34:35] offset:1024
	global_load_dwordx4 v[170:173], v209, s[34:35] offset:2048
	global_load_dwordx4 v[174:177], v209, s[34:35] offset:3072
	s_add_u32 s34, s34, 0x800000
	s_addc_u32 s35, s35, 0
; #define GAS __attribute__((address_space(1)))
; __device__ __forceinline__ void unpack8(const v4u w, float (&f)[8]) { f[0] = bf_lo(w.x); f[1] = bf_hi(w.x); f[2] = bf_lo(w.y); f[3] = bf_hi(w.y); f[4] = bf_lo(w.z); f[5] = bf_hi(w.z); f[6] = bf_lo(w.w); f[7] = bf_hi(w.w); }
; __device__ __forceinline__ void phase_norm(Frame& F, int l, int mode) {
;     ...
;     for (int m = gw; m < M; m += NGW) {
;         float v[4][8];
;         if (from_in) {
; #pragma unroll
;             for (int q = 0; q < 4; ++q) { v[q][0] = nf[q][0].x; v[q][1] = nf[q][0].y; v[q][2] = nf[q][0].z; v[q][3] = nf[q][0].w; v[q][4] = nf[q][1].x; v[q][5] = nf[q][1].y; v[q][6] = nf[q][1].z; v[q][7] = nf[q][1].w; } }
;         else {
; #pragma unroll
;             for (int q = 0; q < 4; ++q) unpack8(nb[q], v[q]); }
;         if (m + NGW < M) NORM_LOAD(m + NGW);
;         const bool slab = (m >= MP) && !from_in;
;         if (slab) { const GAS bf16* SL = (const GAS bf16*)(ws_ + WS_WD) + (size_t)(m - MP) * D;
; #pragma unroll
;             for (int hq = 0; hq < 2; ++hq) {
;                 v4u sv[2][8];
; #pragma unroll
;                 for (int q = 0; q < 2; ++q)
; #pragma unroll
;                     for (int k8 = 0; k8 < 8; ++k8) sv[q][k8] = *(const GAS v4u*)(SL + (size_t)k8 * MS * D + (2 * hq + q) * 512 + lane * 8);
; #pragma unroll
;     ...
;         float s = 0.f;
; #pragma unroll
;         for (int q = 0; q < 4; ++q)
; #pragma unroll
;             for (int j = 0; j < 8; ++j) s += v[q][j] * v[q][j];
;         const float rstd = __builtin_amdgcn_rsqf(wave_sum(s) * (1.f / D) + RMS_EPS);
; #pragma unroll
;         for (int q = 0; q < 4; ++q) { v[q][0] *= rstd * g[q][0].x; v[q][1] *= rstd * g[q][0].y; v[q][2] *= rstd * g[q][0].z; v[q][3] *= rstd * g[q][0].w; v[q][4] *= rstd * g[q][1].x; v[q][5] *= rstd * g[q][1].y; v[q][6] *= rstd * g[q][1].z; v[q][7] *= rstd * g[q][1].w; }
;         if (mode == 2) {
; #pragma unroll
;             for (int q = 0; q < 4; ++q) { GAS f32x4* o = (GAS f32x4*)(out_ + (size_t)m * D + q * 512 + lane * 8); o[0] = (f32x4){v[q][0], v[q][1], v[q][2], v[q][3]}; o[1] = (f32x4){v[q][4], v[q][5], v[q][6], v[q][7]}; }
;             continue; }
; #pragma unroll
;         for (int q = 0; q < 4; ++q) *(GAS v4u*)(HB + (size_t)m * D + q * 512 + lane * 8) = pack8(v[q]);
.Lnf_nl_3:
	v_pk_mul_f32 v[218:219], v[4:5], v[4:5]
	v_pk_fma_f32 v[218:219], v[6:7], v[6:7], v[218:219]
	v_pk_fma_f32 v[218:219], v[8:9], v[8:9], v[218:219]
	v_pk_fma_f32 v[218:219], v[10:11], v[10:11], v[218:219]
	v_pk_fma_f32 v[218:219], v[12:13], v[12:13], v[218:219]
	v_pk_fma_f32 v[218:219], v[14:15], v[14:15], v[218:219]
	v_pk_fma_f32 v[218:219], v[16:17], v[16:17], v[218:219]
	v_pk_fma_f32 v[218:219], v[18:19], v[18:19], v[218:219]
	v_pk_fma_f32 v[218:219], v[20:21], v[20:21], v[218:219]
	v_pk_fma_f32 v[218:219], v[22:23], v[22:23], v[218:219]
	v_pk_fma_f32 v[218:219], v[24:25], v[24:25], v[218:219]
	v_pk_fma_f32 v[218:219], v[26:27], v[26:27], v[218:219]
	v_pk_fma_f32 v[218:219], v[28:29], v[28:29], v[218:219]
	v_pk_fma_f32 v[218:219], v[30:31], v[30:31], v[218:219]
	v_pk_fma_f32 v[218:219], v[32:33], v[32:33], v[218:219]
	v_pk_fma_f32 v[218:219], v[34:35], v[34:35], v[218:219]
	v_add_f32_e32 v211, v218, v219
	s_nop 1
	v_add_f32_dpp v211, v211, v211 quad_perm:[1,0,3,2] row_mask:0xf bank_mask:0xf bound_ctrl:1
	s_nop 1
	v_add_f32_dpp v211, v211, v211 quad_perm:[2,3,0,1] row_mask:0xf bank_mask:0xf bound_ctrl:1
	s_nop 1
	v_add_f32_dpp v211, v211, v211 row_half_mirror row_mask:0xf bank_mask:0xf bound_ctrl:1
	s_nop 1
	v_add_f32_dpp v211, v211, v211 row_mirror row_mask:0xf bank_mask:0xf bound_ctrl:1
	s_nop 1
	v_readlane_b32 s24, v211, 0
	v_readlane_b32 s25, v211, 16
	v_readlane_b32 s62, v211, 32
	v_readlane_b32 s63, v211, 48
	s_nop 1
	v_mov_b32_e32 v212, s25
	v_mov_b32_e32 v214, s63
	v_add_f32_e32 v212, s24, v212
	v_add_f32_e32 v214, s62, v214
	v_add_f32_e32 v212, v212, v214
	v_fmamk_f32 v212, v212, 0x3a000000, v216
	v_rsq_f32_e32 v212, v212
	s_nop 0
	v_pk_mul_f32 v[36:37], v[82:83], v[212:213] op_sel_hi:[1,0]
	v_pk_mul_f32 v[38:39], v[84:85], v[212:213] op_sel_hi:[1,0]
	v_pk_mul_f32 v[40:41], v[86:87], v[212:213] op_sel_hi:[1,0]
	v_pk_mul_f32 v[42:43], v[88:89], v[212:213] op_sel_hi:[1,0]
	v_pk_mul_f32 v[44:45], v[90:91], v[212:213] op_sel_hi:[1,0]
	v_pk_mul_f32 v[46:47], v[92:93], v[212:213] op_sel_hi:[1,0]
	v_pk_mul_f32 v[48:49], v[94:95], v[212:213] op_sel_hi:[1,0]
	v_pk_mul_f32 v[50:51], v[96:97], v[212:213] op_sel_hi:[1,0]
	v_pk_mul_f32 v[52:53], v[98:99], v[212:213] op_sel_hi:[1,0]
	v_pk_mul_f32 v[54:55], v[100:101], v[212:213] op_sel_hi:[1,0]
	v_pk_mul_f32 v[56:57], v[102:103], v[212:213] op_sel_hi:[1,0]
	v_pk_mul_f32 v[58:59], v[104:105], v[212:213] op_sel_hi:[1,0]
	v_pk_mul_f32 v[60:61], v[106:107], v[212:213] op_sel_hi:[1,0]
	v_pk_mul_f32 v[62:63], v[108:109], v[212:213] op_sel_hi:[1,0]
	v_pk_mul_f32 v[64:65], v[110:111], v[212:213] op_sel_hi:[1,0]
	v_pk_mul_f32 v[66:67], v[112:113], v[212:213] op_sel_hi:[1,0]
	v_pk_mul_f32 v[36:37], v[4:5], v[36:37]
	v_pk_mul_f32 v[38:39], v[6:7], v[38:39]
	v_pk_mul_f32 v[40:41], v[8:9], v[40:41]
	v_pk_mul_f32 v[42:43], v[10:11], v[42:43]
	v_pk_mul_f32 v[44:45], v[12:13], v[44:45]
	v_pk_mul_f32 v[46:47], v[14:15], v[46:47]
	v_pk_mul_f32 v[48:49], v[16:17], v[48:49]
	v_pk_mul_f32 v[50:51], v[18:19], v[50:51]
	v_pk_mul_f32 v[52:53], v[20:21], v[52:53]
	v_pk_mul_f32 v[54:55], v[22:23], v[54:55]
	v_pk_mul_f32 v[56:57], v[24:25], v[56:57]
	v_pk_mul_f32 v[58:59], v[26:27], v[58:59]
	v_pk_mul_f32 v[60:61], v[28:29], v[60:61]
	v_pk_mul_f32 v[62:63], v[30:31], v[62:63]
	v_pk_mul_f32 v[64:65], v[32:33], v[64:65]
	v_pk_mul_f32 v[66:67], v[34:35], v[66:67]
	v_cvt_pk_bf16_f32 v178, v36, v37
	v_cvt_pk_bf16_f32 v179, v38, v39
	v_cvt_pk_bf16_f32 v180, v40, v41
	v_cvt_pk_bf16_f32 v181, v42, v43
	v_cvt_pk_bf16_f32 v182, v44, v45
	v_cvt_pk_bf16_f32 v183, v46, v47
	v_cvt_pk_bf16_f32 v184, v48, v49
	v_cvt_pk_bf16_f32 v185, v50, v51
	v_cvt_pk_bf16_f32 v186, v52, v53
	v_cvt_pk_bf16_f32 v187, v54, v55
	v_cvt_pk_bf16_f32 v188, v56, v57
	v_cvt_pk_bf16_f32 v189, v58, v59
	v_cvt_pk_bf16_f32 v190, v60, v61
	v_cvt_pk_bf16_f32 v191, v62, v63
	v_cvt_pk_bf16_f32 v192, v64, v65
	v_cvt_pk_bf16_f32 v193, v66, v67
	global_store_dwordx4 v209, v[178:181], s[36:37] offset:0
	global_store_dwordx4 v209, v[182:185], s[36:37] offset:1024
	global_store_dwordx4 v209, v[186:189], s[36:37] offset:2048
	global_store_dwordx4 v209, v[190:193], s[36:37] offset:3072
	s_add_u32 s36, s36, 0x800000
	s_addc_u32 s37, s37, 0
	s_add_u32 s73, s73, 1
	s_cmp_lt_u32 s73, 2
	s_cbranch_scc1 .Lnf_pass
	s_cmp_eq_u32 s65, 0
	s_cbranch_scc1 .Lnf_ret_norm1
	s_add_i32 s14, s14, 0x4000
	s_cmpk_gt_i32 s14, 0x43ff
	v_readlane_b32 s15, v254, 13
	s_cbranch_scc1 .LBB0_1093
	s_ashr_i32 s15, s14, 31
	s_lshl_b64 s[12:13], s[14:15], 12
	v_lshlrev_b32_e32 v2, 3, v0
	s_add_u32 s0, s8, s12
	v_ashrrev_i32_e32 v3, 31, v2
	s_addc_u32 s1, s9, s13
	v_lshlrev_b64 v[114:115], 1, v[2:3]
	v_lshl_add_u64 v[26:27], s[0:1], 0, v[114:115]
	s_add_u32 s15, s10, 0x3d5a0000
	s_load_dwordx2 s[0:1], s[18:19], 0xb0
	s_addc_u32 s17, s11, 0
	s_cmp_eq_u32 s16, 3
	s_cselect_b32 s19, s17, s9
	s_cselect_b32 s18, s15, s8
	s_ashr_i32 s17, s16, 31
	s_lshl_b64 s[16:17], s[16:17], 13
	s_waitcnt lgkmcnt(0)
	s_add_u32 s0, s0, s16
	s_addc_u32 s1, s1, s17
	v_lshl_add_u64 v[30:31], v[2:3], 2, s[0:1]
	s_mov_b64 s[0:1], 0x1800
	v_lshl_add_u64 v[2:3], v[30:31], 0, s[0:1]
	v_add_co_u32_e32 v10, vcc, s40, v30
	s_mov_b64 s[0:1], 0x1000
	s_nop 0
	v_addc_co_u32_e32 v11, vcc, 0, v31, vcc
	v_lshl_add_u64 v[14:15], v[30:31], 0, s[0:1]
	global_load_dwordx4 v[2:5], v[2:3], off offset:16
	s_nop 0
	global_load_dwordx4 v[6:9], v[10:11], off
	s_nop 0
	global_load_dwordx4 v[10:13], v[10:11], off offset:2048
	s_nop 0
	global_load_dwordx4 v[14:17], v[14:15], off offset:16
	s_nop 0
	global_load_dwordx4 v[18:21], v[30:31], off offset:2064
	global_load_dwordx4 v[22:25], v[30:31], off offset:2048
	global_load_dwordx4 v[54:57], v[26:27], off offset:2048
	global_load_dwordx4 v[50:53], v[26:27], off offset:3072
	global_load_dwordx4 v[62:65], v[26:27], off
	global_load_dwordx4 v[58:61], v[26:27], off offset:1024
	s_nop 0
	global_load_dwordx4 v[26:29], v[30:31], off offset:16
	s_nop 0
	global_load_dwordx4 v[30:33], v[30:31], off
	v_lshl_add_u64 v[34:35], s[10:11], 0, v[114:115]
	s_mov_b64 s[0:1], 0x43ba0000
	v_lshl_add_u64 v[116:117], v[34:35], 0, s[0:1]
	s_add_i32 s0, s44, s14
	s_ashr_i32 s1, s0, 31
	s_lshl_b64 s[0:1], s[0:1], 12
	s_add_u32 s8, s8, s0
	s_addc_u32 s9, s9, s1
	s_add_u32 s0, s10, s12
	s_addc_u32 s1, s11, s13
	s_add_u32 s10, s0, 0x1eb00000
	v_lshl_add_u64 v[118:119], s[18:19], 0, v[114:115]
	s_addc_u32 s11, s1, 0
	s_waitcnt vmcnt(0)
	v_mov_b64_e32 v[38:39], v[54:55]
	v_mov_b64_e32 v[34:35], v[50:51]
	v_mov_b64_e32 v[46:47], v[62:63]
	v_mov_b64_e32 v[42:43], v[58:59]
	v_mov_b64_e32 v[36:37], v[52:53]
	v_mov_b64_e32 v[40:41], v[56:57]
	v_mov_b64_e32 v[44:45], v[60:61]
	v_mov_b64_e32 v[48:49], v[64:65]
	s_branch .LBB0_1087

; #define GAS __attribute__((address_space(1)))
; __device__ __forceinline__ v4u pack8(const float (&f)[8]) { v4u o; o.x = pk2(f[0], f[1]); o.y = pk2(f[2], f[3]); o.z = pk2(f[4], f[5]); o.w = pk2(f[6], f[7]); return o; }
; __device__ __forceinline__ void phase_norm(Frame& F, int l, int mode) {
;     ...
;     f32x4 g[4][2];
; #pragma unroll
;     for (int q = 0; q < 4; ++q) { const GAS f32x4* gp = (const GAS f32x4*)(gain + q * 512 + lane * 8); g[q][0] = gp[0]; g[q][1] = gp[1]; }
;     const bool from_in = (mode == 0 && l == 0);
;     const GAS bf16* XR = (mode == 2) ? XS : XB;
;     GAS bf16* XW = (mode == 1 && l == NL - 1) ? XS : XB;
;     f32x4 nf[4][2]; v4u nb[4];
;     ...
;     if (gw < M) NORM_LOAD(gw);
;     for (int m = gw; m < M; m += NGW) {
;         float v[4][8];
;         if (from_in) {
; #pragma unroll
;             for (int q = 0; q < 4; ++q) { v[q][0] = nf[q][0].x; v[q][1] = nf[q][0].y; v[q][2] = nf[q][0].z; v[q][3] = nf[q][0].w; v[q][4] = nf[q][1].x; v[q][5] = nf[q][1].y; v[q][6] = nf[q][1].z; v[q][7] = nf[q][1].w; } }
;         else {
; #pragma unroll
;             for (int q = 0; q < 4; ++q) unpack8(nb[q], v[q]); }
;         if (m + NGW < M) NORM_LOAD(m + NGW);
;         const bool slab = (m >= MP) && !from_in;
;         if (slab) { const GAS bf16* SL = (const GAS bf16*)(ws_ + WS_WD) + (size_t)(m - MP) * D;
; #pragma unroll
;             for (int hq = 0; hq < 2; ++hq) {
;                 v4u sv[2][8];
; #pragma unroll
;                 for (int q = 0; q < 2; ++q)
; #pragma unroll
;                     for (int k8 = 0; k8 < 8; ++k8) sv[q][k8] = *(const GAS v4u*)(SL + (size_t)k8 * MS * D + (2 * hq + q) * 512 + lane * 8);
; #pragma unroll
;                 for (int q = 0; q < 2; ++q)
; #pragma unroll
;                     for (int k8 = 0; k8 < 8; ++k8) { float p[8]; unpack8(sv[q][k8], p);
; #pragma unroll
;                         for (int j = 0; j < 8; ++j) v[2 * hq + q][j] += p[j]; } } }
;         if (from_in || (slab && mode != 2)) {
; #pragma unroll
;             for (int q = 0; q < 4; ++q) { const v4u w = pack8(v[q]); *(GAS v4u*)(XW + (size_t)m * D + q * 512 + lane * 8) = w; unpack8(w, v[q]); } }
;         float s = 0.f;
; #pragma unroll
;         for (int q = 0; q < 4; ++q)
; #pragma unroll
;             for (int j = 0; j < 8; ++j) s += v[q][j] * v[q][j];
;         const float rstd = __builtin_amdgcn_rsqf(wave_sum(s) * (1.f / D) + RMS_EPS);
.LBB0_1290:
	s_cmp_lt_i32 s50, 50
	s_cselect_b64 s[0:1], -1, 0
	s_cmp_gt_i32 s51, 49
	s_cselect_b64 s[2:3], -1, 0
	s_and_b64 s[0:1], s[0:1], s[2:3]
	s_and_b64 vcc, exec, s[0:1]
	v_readlane_b32 s16, v254, 12
	v_readlane_b32 s17, v254, 13
	s_cbranch_vccz .LBB0_1298
	v_readlane_b32 s0, v254, 0
	v_readlane_b32 s1, v254, 1
	v_mbcnt_lo_u32_b32 v0, -1, 0
	v_mbcnt_hi_u32_b32 v0, -1, v0
	s_nop 0
	v_writelane_b32 v254, s0, 0
	s_nop 1
	v_writelane_b32 v254, s1, 1
	s_nop 0
	v_readlane_b32 s12, v254, 4
	v_readlane_b32 s13, v254, 5
	v_readlane_b32 s14, v254, 6
	v_readlane_b32 s15, v254, 7
	v_readlane_b32 s20, v254, 0
	v_readlane_b32 s21, v254, 1
	s_nop 3
	s_load_dwordx2 s[22:23], s[20:21], 0xc8
	s_load_dwordx4 s[28:31], s[20:21], 0xd0
	v_mbcnt_lo_u32_b32 v208, -1, 0
	v_mbcnt_hi_u32_b32 v208, -1, v208
	v_lshlrev_b32_e32 v209, 4, v208
	v_lshlrev_b32_e32 v210, 5, v208
	v_mov_b32_e32 v216, 0x358637bd
	s_waitcnt lgkmcnt(0)
	s_add_u32 s52, s22, 0x1000
	s_addc_u32 s53, s23, 0
	s_lshl_b32 s24, s16, 12
	s_add_u32 s34, s30, s24
	s_addc_u32 s35, s31, 0
	s_add_u32 s34, s34, 0x3d5a0000
	s_addc_u32 s35, s35, 0
	s_lshl_b32 s24, s16, 13
	s_add_u32 s36, s28, s24
	s_addc_u32 s37, s29, 0
	s_add_u32 s38, s36, 0x1000
	s_addc_u32 s39, s37, 0
	global_load_dwordx4 v[82:85], v210, s[22:23] offset:0
	global_load_dwordx4 v[86:89], v210, s[22:23] offset:16
	global_load_dwordx4 v[90:93], v210, s[22:23] offset:2048
	global_load_dwordx4 v[94:97], v210, s[22:23] offset:2064
	global_load_dwordx4 v[98:101], v210, s[52:53] offset:0
	global_load_dwordx4 v[102:105], v210, s[52:53] offset:16
	global_load_dwordx4 v[106:109], v210, s[52:53] offset:2048
	global_load_dwordx4 v[110:113], v210, s[52:53] offset:2064
	global_load_dwordx4 v[114:117], v209, s[34:35] offset:0
	global_load_dwordx4 v[118:121], v209, s[34:35] offset:1024
	global_load_dwordx4 v[122:125], v209, s[34:35] offset:2048
	global_load_dwordx4 v[126:129], v209, s[34:35] offset:3072
	s_add_u32 s34, s34, 0x800000
	s_addc_u32 s35, s35, 0
	global_load_dwordx4 v[130:133], v209, s[34:35] offset:0
	global_load_dwordx4 v[134:137], v209, s[34:35] offset:1024
	global_load_dwordx4 v[138:141], v209, s[34:35] offset:2048
	global_load_dwordx4 v[142:145], v209, s[34:35] offset:3072
	s_add_u32 s34, s34, 0x800000
	s_addc_u32 s35, s35, 0
	global_load_dwordx4 v[146:149], v209, s[34:35] offset:0
	global_load_dwordx4 v[150:153], v209, s[34:35] offset:1024
	global_load_dwordx4 v[154:157], v209, s[34:35] offset:2048
	global_load_dwordx4 v[158:161], v209, s[34:35] offset:3072
	s_add_u32 s34, s34, 0x800000
	s_addc_u32 s35, s35, 0
	global_load_dwordx4 v[162:165], v209, s[34:35] offset:0
	global_load_dwordx4 v[166:169], v209, s[34:35] offset:1024
	global_load_dwordx4 v[170:173], v209, s[34:35] offset:2048
	global_load_dwordx4 v[174:177], v209, s[34:35] offset:3072
	s_add_u32 s34, s34, 0x800000
	s_addc_u32 s35, s35, 0
	s_waitcnt vmcnt(12)
	v_lshlrev_b32_e32 v4, 16, v114
	v_and_b32_e32 v5, 0xffff0000, v114
	v_lshlrev_b32_e32 v6, 16, v115
	v_and_b32_e32 v7, 0xffff0000, v115
	v_lshlrev_b32_e32 v8, 16, v116
	v_and_b32_e32 v9, 0xffff0000, v116
	v_lshlrev_b32_e32 v10, 16, v117
	v_and_b32_e32 v11, 0xffff0000, v117
	v_lshlrev_b32_e32 v12, 16, v118
	v_and_b32_e32 v13, 0xffff0000, v118
	v_lshlrev_b32_e32 v14, 16, v119
	v_and_b32_e32 v15, 0xffff0000, v119
	v_lshlrev_b32_e32 v16, 16, v120
	v_and_b32_e32 v17, 0xffff0000, v120
	v_lshlrev_b32_e32 v18, 16, v121
	v_and_b32_e32 v19, 0xffff0000, v121
	v_lshlrev_b32_e32 v20, 16, v122
	v_and_b32_e32 v21, 0xffff0000, v122
	v_lshlrev_b32_e32 v22, 16, v123
	v_and_b32_e32 v23, 0xffff0000, v123
	v_lshlrev_b32_e32 v24, 16, v124
	v_and_b32_e32 v25, 0xffff0000, v124
	v_lshlrev_b32_e32 v26, 16, v125
	v_and_b32_e32 v27, 0xffff0000, v125
	v_lshlrev_b32_e32 v28, 16, v126
	v_and_b32_e32 v29, 0xffff0000, v126
	v_lshlrev_b32_e32 v30, 16, v127
	v_and_b32_e32 v31, 0xffff0000, v127
	v_lshlrev_b32_e32 v32, 16, v128
	v_and_b32_e32 v33, 0xffff0000, v128
	v_lshlrev_b32_e32 v34, 16, v129
	v_and_b32_e32 v35, 0xffff0000, v129
	global_load_dwordx4 v[114:117], v209, s[34:35] offset:0
	global_load_dwordx4 v[118:121], v209, s[34:35] offset:1024
	global_load_dwordx4 v[122:125], v209, s[34:35] offset:2048
	global_load_dwordx4 v[126:129], v209, s[34:35] offset:3072
	s_add_u32 s34, s34, 0x800000
	s_addc_u32 s35, s35, 0
	v_pk_mul_f32 v[218:219], v[4:5], v[4:5]
	v_pk_fma_f32 v[218:219], v[6:7], v[6:7], v[218:219]
	v_pk_fma_f32 v[218:219], v[8:9], v[8:9], v[218:219]
	v_pk_fma_f32 v[218:219], v[10:11], v[10:11], v[218:219]
	v_pk_fma_f32 v[218:219], v[12:13], v[12:13], v[218:219]
	v_pk_fma_f32 v[218:219], v[14:15], v[14:15], v[218:219]
	v_pk_fma_f32 v[218:219], v[16:17], v[16:17], v[218:219]
	v_pk_fma_f32 v[218:219], v[18:19], v[18:19], v[218:219]
	v_pk_fma_f32 v[218:219], v[20:21], v[20:21], v[218:219]
	v_pk_fma_f32 v[218:219], v[22:23], v[22:23], v[218:219]
	v_pk_fma_f32 v[218:219], v[24:25], v[24:25], v[218:219]
	v_pk_fma_f32 v[218:219], v[26:27], v[26:27], v[218:219]
	v_pk_fma_f32 v[218:219], v[28:29], v[28:29], v[218:219]
	v_pk_fma_f32 v[218:219], v[30:31], v[30:31], v[218:219]
	v_pk_fma_f32 v[218:219], v[32:33], v[32:33], v[218:219]
	v_pk_fma_f32 v[218:219], v[34:35], v[34:35], v[218:219]
	v_add_f32_e32 v211, v218, v219
	s_nop 1
	v_add_f32_dpp v211, v211, v211 quad_perm:[1,0,3,2] row_mask:0xf bank_mask:0xf bound_ctrl:1
	s_nop 1
	v_add_f32_dpp v211, v211, v211 quad_perm:[2,3,0,1] row_mask:0xf bank_mask:0xf bound_ctrl:1
	s_nop 1
	v_add_f32_dpp v211, v211, v211 row_half_mirror row_mask:0xf bank_mask:0xf bound_ctrl:1
	s_nop 1
	v_add_f32_dpp v211, v211, v211 row_mirror row_mask:0xf bank_mask:0xf bound_ctrl:1
	s_nop 1
	v_readlane_b32 s24, v211, 0
; #define GAS __attribute__((address_space(1)))
; __device__ __forceinline__ void unpack8(const v4u w, float (&f)[8]) { f[0] = bf_lo(w.x); f[1] = bf_hi(w.x); f[2] = bf_lo(w.y); f[3] = bf_hi(w.y); f[4] = bf_lo(w.z); f[5] = bf_hi(w.z); f[6] = bf_lo(w.w); f[7] = bf_hi(w.w); }
; __device__ __forceinline__ void phase_norm(Frame& F, int l, int mode) {
;     ...
;         else {
; #pragma unroll
;             for (int q = 0; q < 4; ++q) unpack8(nb[q], v[q]); }
;         if (m + NGW < M) NORM_LOAD(m + NGW);
;     ...
;         float s = 0.f;
; #pragma unroll
;         for (int q = 0; q < 4; ++q)
; #pragma unroll
;             for (int j = 0; j < 8; ++j) s += v[q][j] * v[q][j];
;         const float rstd = __builtin_amdgcn_rsqf(wave_sum(s) * (1.f / D) + RMS_EPS);
; #pragma unroll
;         for (int q = 0; q < 4; ++q) { v[q][0] *= rstd * g[q][0].x; v[q][1] *= rstd * g[q][0].y; v[q][2] *= rstd * g[q][0].z; v[q][3] *= rstd * g[q][0].w; v[q][4] *= rstd * g[q][1].x; v[q][5] *= rstd * g[q][1].y; v[q][6] *= rstd * g[q][1].z; v[q][7] *= rstd * g[q][1].w; }
;         if (mode == 2) {
; #pragma unroll
;             for (int q = 0; q < 4; ++q) { GAS f32x4* o = (GAS f32x4*)(out_ + (size_t)m * D + q * 512 + lane * 8); o[0] = (f32x4){v[q][0], v[q][1], v[q][2], v[q][3]}; o[1] = (f32x4){v[q][4], v[q][5], v[q][6], v[q][7]}; }
;             continue; }
	v_readlane_b32 s25, v211, 16
	v_readlane_b32 s62, v211, 32
	v_readlane_b32 s63, v211, 48
	s_nop 1
	v_mov_b32_e32 v212, s25
	v_mov_b32_e32 v214, s63
	v_add_f32_e32 v212, s24, v212
	v_add_f32_e32 v214, s62, v214
	v_add_f32_e32 v212, v212, v214
	v_fmamk_f32 v212, v212, 0x3a000000, v216
	v_rsq_f32_e32 v212, v212
	s_nop 0
	v_pk_mul_f32 v[36:37], v[82:83], v[212:213] op_sel_hi:[1,0]
	v_pk_mul_f32 v[38:39], v[84:85], v[212:213] op_sel_hi:[1,0]
	v_pk_mul_f32 v[40:41], v[86:87], v[212:213] op_sel_hi:[1,0]
	v_pk_mul_f32 v[42:43], v[88:89], v[212:213] op_sel_hi:[1,0]
	v_pk_mul_f32 v[44:45], v[90:91], v[212:213] op_sel_hi:[1,0]
	v_pk_mul_f32 v[46:47], v[92:93], v[212:213] op_sel_hi:[1,0]
	v_pk_mul_f32 v[48:49], v[94:95], v[212:213] op_sel_hi:[1,0]
	v_pk_mul_f32 v[50:51], v[96:97], v[212:213] op_sel_hi:[1,0]
	v_pk_mul_f32 v[52:53], v[98:99], v[212:213] op_sel_hi:[1,0]
	v_pk_mul_f32 v[54:55], v[100:101], v[212:213] op_sel_hi:[1,0]
	v_pk_mul_f32 v[56:57], v[102:103], v[212:213] op_sel_hi:[1,0]
	v_pk_mul_f32 v[58:59], v[104:105], v[212:213] op_sel_hi:[1,0]
	v_pk_mul_f32 v[60:61], v[106:107], v[212:213] op_sel_hi:[1,0]
	v_pk_mul_f32 v[62:63], v[108:109], v[212:213] op_sel_hi:[1,0]
	v_pk_mul_f32 v[64:65], v[110:111], v[212:213] op_sel_hi:[1,0]
	v_pk_mul_f32 v[66:67], v[112:113], v[212:213] op_sel_hi:[1,0]
	v_pk_mul_f32 v[36:37], v[4:5], v[36:37]
	v_pk_mul_f32 v[38:39], v[6:7], v[38:39]
	v_pk_mul_f32 v[40:41], v[8:9], v[40:41]
	v_pk_mul_f32 v[42:43], v[10:11], v[42:43]
	v_pk_mul_f32 v[44:45], v[12:13], v[44:45]
	v_pk_mul_f32 v[46:47], v[14:15], v[46:47]
	v_pk_mul_f32 v[48:49], v[16:17], v[48:49]
	v_pk_mul_f32 v[50:51], v[18:19], v[50:51]
	v_pk_mul_f32 v[52:53], v[20:21], v[52:53]
	v_pk_mul_f32 v[54:55], v[22:23], v[54:55]
	v_pk_mul_f32 v[56:57], v[24:25], v[56:57]
	v_pk_mul_f32 v[58:59], v[26:27], v[58:59]
	v_pk_mul_f32 v[60:61], v[28:29], v[60:61]
	v_pk_mul_f32 v[62:63], v[30:31], v[62:63]
	v_pk_mul_f32 v[64:65], v[32:33], v[64:65]
	v_pk_mul_f32 v[66:67], v[34:35], v[66:67]
	global_store_dwordx4 v210, v[36:39], s[36:37] offset:0
	global_store_dwordx4 v210, v[40:43], s[36:37] offset:16
	global_store_dwordx4 v210, v[44:47], s[36:37] offset:2048
	global_store_dwordx4 v210, v[48:51], s[36:37] offset:2064
	global_store_dwordx4 v210, v[52:55], s[38:39] offset:0
	global_store_dwordx4 v210, v[56:59], s[38:39] offset:16
	global_store_dwordx4 v210, v[60:63], s[38:39] offset:2048
	global_store_dwordx4 v210, v[64:67], s[38:39] offset:2064
	s_add_u32 s36, s36, 0x1000000
	s_addc_u32 s37, s37, 0
	s_add_u32 s38, s38, 0x1000000
	s_addc_u32 s39, s39, 0
	s_waitcnt vmcnt(20)
	v_lshlrev_b32_e32 v4, 16, v130
	v_and_b32_e32 v5, 0xffff0000, v130
	v_lshlrev_b32_e32 v6, 16, v131
	v_and_b32_e32 v7, 0xffff0000, v131
	v_lshlrev_b32_e32 v8, 16, v132
	v_and_b32_e32 v9, 0xffff0000, v132
	v_lshlrev_b32_e32 v10, 16, v133
	v_and_b32_e32 v11, 0xffff0000, v133
	v_lshlrev_b32_e32 v12, 16, v134
	v_and_b32_e32 v13, 0xffff0000, v134
	v_lshlrev_b32_e32 v14, 16, v135
	v_and_b32_e32 v15, 0xffff0000, v135
	v_lshlrev_b32_e32 v16, 16, v136
	v_and_b32_e32 v17, 0xffff0000, v136
	v_lshlrev_b32_e32 v18, 16, v137
	v_and_b32_e32 v19, 0xffff0000, v137
	v_lshlrev_b32_e32 v20, 16, v138
	v_and_b32_e32 v21, 0xffff0000, v138
	v_lshlrev_b32_e32 v22, 16, v139
	v_and_b32_e32 v23, 0xffff0000, v139
	v_lshlrev_b32_e32 v24, 16, v140
	v_and_b32_e32 v25, 0xffff0000, v140
	v_lshlrev_b32_e32 v26, 16, v141
	v_and_b32_e32 v27, 0xffff0000, v141
	v_lshlrev_b32_e32 v28, 16, v142
	v_and_b32_e32 v29, 0xffff0000, v142
	v_lshlrev_b32_e32 v30, 16, v143
	v_and_b32_e32 v31, 0xffff0000, v143
	v_lshlrev_b32_e32 v32, 16, v144
	v_and_b32_e32 v33, 0xffff0000, v144
	v_lshlrev_b32_e32 v34, 16, v145
	v_and_b32_e32 v35, 0xffff0000, v145
	global_load_dwordx4 v[130:133], v209, s[34:35] offset:0
	global_load_dwordx4 v[134:137], v209, s[34:35] offset:1024
	global_load_dwordx4 v[138:141], v209, s[34:35] offset:2048
	global_load_dwordx4 v[142:145], v209, s[34:35] offset:3072
	s_add_u32 s34, s34, 0x800000
	s_addc_u32 s35, s35, 0
	v_pk_mul_f32 v[218:219], v[4:5], v[4:5]
	v_pk_fma_f32 v[218:219], v[6:7], v[6:7], v[218:219]
	v_pk_fma_f32 v[218:219], v[8:9], v[8:9], v[218:219]
	v_pk_fma_f32 v[218:219], v[10:11], v[10:11], v[218:219]
	v_pk_fma_f32 v[218:219], v[12:13], v[12:13], v[218:219]
	v_pk_fma_f32 v[218:219], v[14:15], v[14:15], v[218:219]
	v_pk_fma_f32 v[218:219], v[16:17], v[16:17], v[218:219]
	v_pk_fma_f32 v[218:219], v[18:19], v[18:19], v[218:219]
	v_pk_fma_f32 v[218:219], v[20:21], v[20:21], v[218:219]
	v_pk_fma_f32 v[218:219], v[22:23], v[22:23], v[218:219]
	v_pk_fma_f32 v[218:219], v[24:25], v[24:25], v[218:219]
	v_pk_fma_f32 v[218:219], v[26:27], v[26:27], v[218:219]
	v_pk_fma_f32 v[218:219], v[28:29], v[28:29], v[218:219]
	v_pk_fma_f32 v[218:219], v[30:31], v[30:31], v[218:219]
	v_pk_fma_f32 v[218:219], v[32:33], v[32:33], v[218:219]
	v_pk_fma_f32 v[218:219], v[34:35], v[34:35], v[218:219]
	v_add_f32_e32 v211, v218, v219
	s_nop 1
	v_add_f32_dpp v211, v211, v211 quad_perm:[1,0,3,2] row_mask:0xf bank_mask:0xf bound_ctrl:1
	s_nop 1
	v_add_f32_dpp v211, v211, v211 quad_perm:[2,3,0,1] row_mask:0xf bank_mask:0xf bound_ctrl:1
	s_nop 1
	v_add_f32_dpp v211, v211, v211 row_half_mirror row_mask:0xf bank_mask:0xf bound_ctrl:1
	s_nop 1
	v_add_f32_dpp v211, v211, v211 row_mirror row_mask:0xf bank_mask:0xf bound_ctrl:1
	s_nop 1
	v_readlane_b32 s24, v211, 0
	v_readlane_b32 s25, v211, 16
	v_readlane_b32 s62, v211, 32
	v_readlane_b32 s63, v211, 48
	s_nop 1
	v_mov_b32_e32 v212, s25
	v_mov_b32_e32 v214, s63
	v_add_f32_e32 v212, s24, v212
	v_add_f32_e32 v214, s62, v214
	v_add_f32_e32 v212, v212, v214
	v_fmamk_f32 v212, v212, 0x3a000000, v216
	v_rsq_f32_e32 v212, v212
; #define GAS __attribute__((address_space(1)))
; __device__ __forceinline__ void unpack8(const v4u w, float (&f)[8]) { f[0] = bf_lo(w.x); f[1] = bf_hi(w.x); f[2] = bf_lo(w.y); f[3] = bf_hi(w.y); f[4] = bf_lo(w.z); f[5] = bf_hi(w.z); f[6] = bf_lo(w.w); f[7] = bf_hi(w.w); }
; __device__ __forceinline__ void phase_norm(Frame& F, int l, int mode) {
;     ...
;         else {
; #pragma unroll
;             for (int q = 0; q < 4; ++q) unpack8(nb[q], v[q]); }
;         if (m + NGW < M) NORM_LOAD(m + NGW);
;     ...
;         float s = 0.f;
; #pragma unroll
;         for (int q = 0; q < 4; ++q)
; #pragma unroll
;             for (int j = 0; j < 8; ++j) s += v[q][j] * v[q][j];
;         const float rstd = __builtin_amdgcn_rsqf(wave_sum(s) * (1.f / D) + RMS_EPS);
; #pragma unroll
;         for (int q = 0; q < 4; ++q) { v[q][0] *= rstd * g[q][0].x; v[q][1] *= rstd * g[q][0].y; v[q][2] *= rstd * g[q][0].z; v[q][3] *= rstd * g[q][0].w; v[q][4] *= rstd * g[q][1].x; v[q][5] *= rstd * g[q][1].y; v[q][6] *= rstd * g[q][1].z; v[q][7] *= rstd * g[q][1].w; }
;         if (mode == 2) {
; #pragma unroll
;             for (int q = 0; q < 4; ++q) { GAS f32x4* o = (GAS f32x4*)(out_ + (size_t)m * D + q * 512 + lane * 8); o[0] = (f32x4){v[q][0], v[q][1], v[q][2], v[q][3]}; o[1] = (f32x4){v[q][4], v[q][5], v[q][6], v[q][7]}; }
;             continue; }
	s_nop 0
	v_pk_mul_f32 v[36:37], v[82:83], v[212:213] op_sel_hi:[1,0]
	v_pk_mul_f32 v[38:39], v[84:85], v[212:213] op_sel_hi:[1,0]
	v_pk_mul_f32 v[40:41], v[86:87], v[212:213] op_sel_hi:[1,0]
	v_pk_mul_f32 v[42:43], v[88:89], v[212:213] op_sel_hi:[1,0]
	v_pk_mul_f32 v[44:45], v[90:91], v[212:213] op_sel_hi:[1,0]
	v_pk_mul_f32 v[46:47], v[92:93], v[212:213] op_sel_hi:[1,0]
	v_pk_mul_f32 v[48:49], v[94:95], v[212:213] op_sel_hi:[1,0]
	v_pk_mul_f32 v[50:51], v[96:97], v[212:213] op_sel_hi:[1,0]
	v_pk_mul_f32 v[52:53], v[98:99], v[212:213] op_sel_hi:[1,0]
	v_pk_mul_f32 v[54:55], v[100:101], v[212:213] op_sel_hi:[1,0]
	v_pk_mul_f32 v[56:57], v[102:103], v[212:213] op_sel_hi:[1,0]
	v_pk_mul_f32 v[58:59], v[104:105], v[212:213] op_sel_hi:[1,0]
	v_pk_mul_f32 v[60:61], v[106:107], v[212:213] op_sel_hi:[1,0]
	v_pk_mul_f32 v[62:63], v[108:109], v[212:213] op_sel_hi:[1,0]
	v_pk_mul_f32 v[64:65], v[110:111], v[212:213] op_sel_hi:[1,0]
	v_pk_mul_f32 v[66:67], v[112:113], v[212:213] op_sel_hi:[1,0]
	v_pk_mul_f32 v[36:37], v[4:5], v[36:37]
	v_pk_mul_f32 v[38:39], v[6:7], v[38:39]
	v_pk_mul_f32 v[40:41], v[8:9], v[40:41]
	v_pk_mul_f32 v[42:43], v[10:11], v[42:43]
	v_pk_mul_f32 v[44:45], v[12:13], v[44:45]
	v_pk_mul_f32 v[46:47], v[14:15], v[46:47]
	v_pk_mul_f32 v[48:49], v[16:17], v[48:49]
	v_pk_mul_f32 v[50:51], v[18:19], v[50:51]
	v_pk_mul_f32 v[52:53], v[20:21], v[52:53]
	v_pk_mul_f32 v[54:55], v[22:23], v[54:55]
	v_pk_mul_f32 v[56:57], v[24:25], v[56:57]
	v_pk_mul_f32 v[58:59], v[26:27], v[58:59]
	v_pk_mul_f32 v[60:61], v[28:29], v[60:61]
	v_pk_mul_f32 v[62:63], v[30:31], v[62:63]
	v_pk_mul_f32 v[64:65], v[32:33], v[64:65]
	v_pk_mul_f32 v[66:67], v[34:35], v[66:67]
	global_store_dwordx4 v210, v[36:39], s[36:37] offset:0
	global_store_dwordx4 v210, v[40:43], s[36:37] offset:16
	global_store_dwordx4 v210, v[44:47], s[36:37] offset:2048
	global_store_dwordx4 v210, v[48:51], s[36:37] offset:2064
	global_store_dwordx4 v210, v[52:55], s[38:39] offset:0
	global_store_dwordx4 v210, v[56:59], s[38:39] offset:16
	global_store_dwordx4 v210, v[60:63], s[38:39] offset:2048
	global_store_dwordx4 v210, v[64:67], s[38:39] offset:2064
	s_add_u32 s36, s36, 0x1000000
	s_addc_u32 s37, s37, 0
	s_add_u32 s38, s38, 0x1000000
	s_addc_u32 s39, s39, 0
	s_waitcnt vmcnt(28)
	v_lshlrev_b32_e32 v4, 16, v146
	v_and_b32_e32 v5, 0xffff0000, v146
	v_lshlrev_b32_e32 v6, 16, v147
	v_and_b32_e32 v7, 0xffff0000, v147
	v_lshlrev_b32_e32 v8, 16, v148
	v_and_b32_e32 v9, 0xffff0000, v148
	v_lshlrev_b32_e32 v10, 16, v149
	v_and_b32_e32 v11, 0xffff0000, v149
	v_lshlrev_b32_e32 v12, 16, v150
	v_and_b32_e32 v13, 0xffff0000, v150
	v_lshlrev_b32_e32 v14, 16, v151
	v_and_b32_e32 v15, 0xffff0000, v151
	v_lshlrev_b32_e32 v16, 16, v152
	v_and_b32_e32 v17, 0xffff0000, v152
	v_lshlrev_b32_e32 v18, 16, v153
	v_and_b32_e32 v19, 0xffff0000, v153
	v_lshlrev_b32_e32 v20, 16, v154
	v_and_b32_e32 v21, 0xffff0000, v154
	v_lshlrev_b32_e32 v22, 16, v155
	v_and_b32_e32 v23, 0xffff0000, v155
	v_lshlrev_b32_e32 v24, 16, v156
	v_and_b32_e32 v25, 0xffff0000, v156
	v_lshlrev_b32_e32 v26, 16, v157
	v_and_b32_e32 v27, 0xffff0000, v157
	v_lshlrev_b32_e32 v28, 16, v158
	v_and_b32_e32 v29, 0xffff0000, v158
	v_lshlrev_b32_e32 v30, 16, v159
	v_and_b32_e32 v31, 0xffff0000, v159
	v_lshlrev_b32_e32 v32, 16, v160
	v_and_b32_e32 v33, 0xffff0000, v160
	v_lshlrev_b32_e32 v34, 16, v161
	v_and_b32_e32 v35, 0xffff0000, v161
	global_load_dwordx4 v[146:149], v209, s[34:35] offset:0
	global_load_dwordx4 v[150:153], v209, s[34:35] offset:1024
	global_load_dwordx4 v[154:157], v209, s[34:35] offset:2048
	global_load_dwordx4 v[158:161], v209, s[34:35] offset:3072
	s_add_u32 s34, s34, 0x800000
	s_addc_u32 s35, s35, 0
	v_pk_mul_f32 v[218:219], v[4:5], v[4:5]
	v_pk_fma_f32 v[218:219], v[6:7], v[6:7], v[218:219]
	v_pk_fma_f32 v[218:219], v[8:9], v[8:9], v[218:219]
	v_pk_fma_f32 v[218:219], v[10:11], v[10:11], v[218:219]
	v_pk_fma_f32 v[218:219], v[12:13], v[12:13], v[218:219]
	v_pk_fma_f32 v[218:219], v[14:15], v[14:15], v[218:219]
	v_pk_fma_f32 v[218:219], v[16:17], v[16:17], v[218:219]
	v_pk_fma_f32 v[218:219], v[18:19], v[18:19], v[218:219]
	v_pk_fma_f32 v[218:219], v[20:21], v[20:21], v[218:219]
	v_pk_fma_f32 v[218:219], v[22:23], v[22:23], v[218:219]
	v_pk_fma_f32 v[218:219], v[24:25], v[24:25], v[218:219]
	v_pk_fma_f32 v[218:219], v[26:27], v[26:27], v[218:219]
	v_pk_fma_f32 v[218:219], v[28:29], v[28:29], v[218:219]
	v_pk_fma_f32 v[218:219], v[30:31], v[30:31], v[218:219]
	v_pk_fma_f32 v[218:219], v[32:33], v[32:33], v[218:219]
	v_pk_fma_f32 v[218:219], v[34:35], v[34:35], v[218:219]
	v_add_f32_e32 v211, v218, v219
	s_nop 1
	v_add_f32_dpp v211, v211, v211 quad_perm:[1,0,3,2] row_mask:0xf bank_mask:0xf bound_ctrl:1
	s_nop 1
	v_add_f32_dpp v211, v211, v211 quad_perm:[2,3,0,1] row_mask:0xf bank_mask:0xf bound_ctrl:1
	s_nop 1
	v_add_f32_dpp v211, v211, v211 row_half_mirror row_mask:0xf bank_mask:0xf bound_ctrl:1
	s_nop 1
	v_add_f32_dpp v211, v211, v211 row_mirror row_mask:0xf bank_mask:0xf bound_ctrl:1
	s_nop 1
	v_readlane_b32 s24, v211, 0
	v_readlane_b32 s25, v211, 16
	v_readlane_b32 s62, v211, 32
	v_readlane_b32 s63, v211, 48
	s_nop 1
	v_mov_b32_e32 v212, s25
	v_mov_b32_e32 v214, s63
	v_add_f32_e32 v212, s24, v212
	v_add_f32_e32 v214, s62, v214
	v_add_f32_e32 v212, v212, v214
	v_fmamk_f32 v212, v212, 0x3a000000, v216
	v_rsq_f32_e32 v212, v212
	s_nop 0
	v_pk_mul_f32 v[36:37], v[82:83], v[212:213] op_sel_hi:[1,0]
	v_pk_mul_f32 v[38:39], v[84:85], v[212:213] op_sel_hi:[1,0]
	v_pk_mul_f32 v[40:41], v[86:87], v[212:213] op_sel_hi:[1,0]
	v_pk_mul_f32 v[42:43], v[88:89], v[212:213] op_sel_hi:[1,0]
	v_pk_mul_f32 v[44:45], v[90:91], v[212:213] op_sel_hi:[1,0]
; #define GAS __attribute__((address_space(1)))
; __device__ __forceinline__ void unpack8(const v4u w, float (&f)[8]) { f[0] = bf_lo(w.x); f[1] = bf_hi(w.x); f[2] = bf_lo(w.y); f[3] = bf_hi(w.y); f[4] = bf_lo(w.z); f[5] = bf_hi(w.z); f[6] = bf_lo(w.w); f[7] = bf_hi(w.w); }
; __device__ __forceinline__ void phase_norm(Frame& F, int l, int mode) {
;     ...
;         else {
; #pragma unroll
;             for (int q = 0; q < 4; ++q) unpack8(nb[q], v[q]); }
;         if (m + NGW < M) NORM_LOAD(m + NGW);
;     ...
;         float s = 0.f;
; #pragma unroll
;         for (int q = 0; q < 4; ++q)
; #pragma unroll
;             for (int j = 0; j < 8; ++j) s += v[q][j] * v[q][j];
;         const float rstd = __builtin_amdgcn_rsqf(wave_sum(s) * (1.f / D) + RMS_EPS);
; #pragma unroll
;         for (int q = 0; q < 4; ++q) { v[q][0] *= rstd * g[q][0].x; v[q][1] *= rstd * g[q][0].y; v[q][2] *= rstd * g[q][0].z; v[q][3] *= rstd * g[q][0].w; v[q][4] *= rstd * g[q][1].x; v[q][5] *= rstd * g[q][1].y; v[q][6] *= rstd * g[q][1].z; v[q][7] *= rstd * g[q][1].w; }
;         if (mode == 2) {
; #pragma unroll
;             for (int q = 0; q < 4; ++q) { GAS f32x4* o = (GAS f32x4*)(out_ + (size_t)m * D + q * 512 + lane * 8); o[0] = (f32x4){v[q][0], v[q][1], v[q][2], v[q][3]}; o[1] = (f32x4){v[q][4], v[q][5], v[q][6], v[q][7]}; }
;             continue; }
	v_pk_mul_f32 v[46:47], v[92:93], v[212:213] op_sel_hi:[1,0]
	v_pk_mul_f32 v[48:49], v[94:95], v[212:213] op_sel_hi:[1,0]
	v_pk_mul_f32 v[50:51], v[96:97], v[212:213] op_sel_hi:[1,0]
	v_pk_mul_f32 v[52:53], v[98:99], v[212:213] op_sel_hi:[1,0]
	v_pk_mul_f32 v[54:55], v[100:101], v[212:213] op_sel_hi:[1,0]
	v_pk_mul_f32 v[56:57], v[102:103], v[212:213] op_sel_hi:[1,0]
	v_pk_mul_f32 v[58:59], v[104:105], v[212:213] op_sel_hi:[1,0]
	v_pk_mul_f32 v[60:61], v[106:107], v[212:213] op_sel_hi:[1,0]
	v_pk_mul_f32 v[62:63], v[108:109], v[212:213] op_sel_hi:[1,0]
	v_pk_mul_f32 v[64:65], v[110:111], v[212:213] op_sel_hi:[1,0]
	v_pk_mul_f32 v[66:67], v[112:113], v[212:213] op_sel_hi:[1,0]
	v_pk_mul_f32 v[36:37], v[4:5], v[36:37]
	v_pk_mul_f32 v[38:39], v[6:7], v[38:39]
	v_pk_mul_f32 v[40:41], v[8:9], v[40:41]
	v_pk_mul_f32 v[42:43], v[10:11], v[42:43]
	v_pk_mul_f32 v[44:45], v[12:13], v[44:45]
	v_pk_mul_f32 v[46:47], v[14:15], v[46:47]
	v_pk_mul_f32 v[48:49], v[16:17], v[48:49]
	v_pk_mul_f32 v[50:51], v[18:19], v[50:51]
	v_pk_mul_f32 v[52:53], v[20:21], v[52:53]
	v_pk_mul_f32 v[54:55], v[22:23], v[54:55]
	v_pk_mul_f32 v[56:57], v[24:25], v[56:57]
	v_pk_mul_f32 v[58:59], v[26:27], v[58:59]
	v_pk_mul_f32 v[60:61], v[28:29], v[60:61]
	v_pk_mul_f32 v[62:63], v[30:31], v[62:63]
	v_pk_mul_f32 v[64:65], v[32:33], v[64:65]
	v_pk_mul_f32 v[66:67], v[34:35], v[66:67]
	global_store_dwordx4 v210, v[36:39], s[36:37] offset:0
	global_store_dwordx4 v210, v[40:43], s[36:37] offset:16
	global_store_dwordx4 v210, v[44:47], s[36:37] offset:2048
	global_store_dwordx4 v210, v[48:51], s[36:37] offset:2064
	global_store_dwordx4 v210, v[52:55], s[38:39] offset:0
	global_store_dwordx4 v210, v[56:59], s[38:39] offset:16
	global_store_dwordx4 v210, v[60:63], s[38:39] offset:2048
	global_store_dwordx4 v210, v[64:67], s[38:39] offset:2064
	s_add_u32 s36, s36, 0x1000000
	s_addc_u32 s37, s37, 0
	s_add_u32 s38, s38, 0x1000000
	s_addc_u32 s39, s39, 0
	s_waitcnt vmcnt(36)
	v_lshlrev_b32_e32 v4, 16, v162
	v_and_b32_e32 v5, 0xffff0000, v162
	v_lshlrev_b32_e32 v6, 16, v163
	v_and_b32_e32 v7, 0xffff0000, v163
	v_lshlrev_b32_e32 v8, 16, v164
	v_and_b32_e32 v9, 0xffff0000, v164
	v_lshlrev_b32_e32 v10, 16, v165
	v_and_b32_e32 v11, 0xffff0000, v165
	v_lshlrev_b32_e32 v12, 16, v166
	v_and_b32_e32 v13, 0xffff0000, v166
	v_lshlrev_b32_e32 v14, 16, v167
	v_and_b32_e32 v15, 0xffff0000, v167
	v_lshlrev_b32_e32 v16, 16, v168
	v_and_b32_e32 v17, 0xffff0000, v168
	v_lshlrev_b32_e32 v18, 16, v169
	v_and_b32_e32 v19, 0xffff0000, v169
	v_lshlrev_b32_e32 v20, 16, v170
	v_and_b32_e32 v21, 0xffff0000, v170
	v_lshlrev_b32_e32 v22, 16, v171
	v_and_b32_e32 v23, 0xffff0000, v171
	v_lshlrev_b32_e32 v24, 16, v172
	v_and_b32_e32 v25, 0xffff0000, v172
	v_lshlrev_b32_e32 v26, 16, v173
	v_and_b32_e32 v27, 0xffff0000, v173
	v_lshlrev_b32_e32 v28, 16, v174
	v_and_b32_e32 v29, 0xffff0000, v174
	v_lshlrev_b32_e32 v30, 16, v175
	v_and_b32_e32 v31, 0xffff0000, v175
	v_lshlrev_b32_e32 v32, 16, v176
	v_and_b32_e32 v33, 0xffff0000, v176
	v_lshlrev_b32_e32 v34, 16, v177
	v_and_b32_e32 v35, 0xffff0000, v177
	global_load_dwordx4 v[162:165], v209, s[34:35] offset:0
	global_load_dwordx4 v[166:169], v209, s[34:35] offset:1024
	global_load_dwordx4 v[170:173], v209, s[34:35] offset:2048
	global_load_dwordx4 v[174:177], v209, s[34:35] offset:3072
	s_add_u32 s34, s34, 0x800000
	s_addc_u32 s35, s35, 0
	v_pk_mul_f32 v[218:219], v[4:5], v[4:5]
	v_pk_fma_f32 v[218:219], v[6:7], v[6:7], v[218:219]
	v_pk_fma_f32 v[218:219], v[8:9], v[8:9], v[218:219]
	v_pk_fma_f32 v[218:219], v[10:11], v[10:11], v[218:219]
	v_pk_fma_f32 v[218:219], v[12:13], v[12:13], v[218:219]
	v_pk_fma_f32 v[218:219], v[14:15], v[14:15], v[218:219]
	v_pk_fma_f32 v[218:219], v[16:17], v[16:17], v[218:219]
	v_pk_fma_f32 v[218:219], v[18:19], v[18:19], v[218:219]
	v_pk_fma_f32 v[218:219], v[20:21], v[20:21], v[218:219]
	v_pk_fma_f32 v[218:219], v[22:23], v[22:23], v[218:219]
	v_pk_fma_f32 v[218:219], v[24:25], v[24:25], v[218:219]
	v_pk_fma_f32 v[218:219], v[26:27], v[26:27], v[218:219]
	v_pk_fma_f32 v[218:219], v[28:29], v[28:29], v[218:219]
	v_pk_fma_f32 v[218:219], v[30:31], v[30:31], v[218:219]
	v_pk_fma_f32 v[218:219], v[32:33], v[32:33], v[218:219]
	v_pk_fma_f32 v[218:219], v[34:35], v[34:35], v[218:219]
	v_add_f32_e32 v211, v218, v219
	s_nop 1
	v_add_f32_dpp v211, v211, v211 quad_perm:[1,0,3,2] row_mask:0xf bank_mask:0xf bound_ctrl:1
	s_nop 1
	v_add_f32_dpp v211, v211, v211 quad_perm:[2,3,0,1] row_mask:0xf bank_mask:0xf bound_ctrl:1
	s_nop 1
	v_add_f32_dpp v211, v211, v211 row_half_mirror row_mask:0xf bank_mask:0xf bound_ctrl:1
	s_nop 1
	v_add_f32_dpp v211, v211, v211 row_mirror row_mask:0xf bank_mask:0xf bound_ctrl:1
	s_nop 1
	v_readlane_b32 s24, v211, 0
	v_readlane_b32 s25, v211, 16
	v_readlane_b32 s62, v211, 32
	v_readlane_b32 s63, v211, 48
	s_nop 1
	v_mov_b32_e32 v212, s25
	v_mov_b32_e32 v214, s63
	v_add_f32_e32 v212, s24, v212
	v_add_f32_e32 v214, s62, v214
	v_add_f32_e32 v212, v212, v214
	v_fmamk_f32 v212, v212, 0x3a000000, v216
	v_rsq_f32_e32 v212, v212
	s_nop 0
	v_pk_mul_f32 v[36:37], v[82:83], v[212:213] op_sel_hi:[1,0]
	v_pk_mul_f32 v[38:39], v[84:85], v[212:213] op_sel_hi:[1,0]
	v_pk_mul_f32 v[40:41], v[86:87], v[212:213] op_sel_hi:[1,0]
	v_pk_mul_f32 v[42:43], v[88:89], v[212:213] op_sel_hi:[1,0]
	v_pk_mul_f32 v[44:45], v[90:91], v[212:213] op_sel_hi:[1,0]
	v_pk_mul_f32 v[46:47], v[92:93], v[212:213] op_sel_hi:[1,0]
	v_pk_mul_f32 v[48:49], v[94:95], v[212:213] op_sel_hi:[1,0]
	v_pk_mul_f32 v[50:51], v[96:97], v[212:213] op_sel_hi:[1,0]
	v_pk_mul_f32 v[52:53], v[98:99], v[212:213] op_sel_hi:[1,0]
	v_pk_mul_f32 v[54:55], v[100:101], v[212:213] op_sel_hi:[1,0]
; #define GAS __attribute__((address_space(1)))
; __device__ __forceinline__ void unpack8(const v4u w, float (&f)[8]) { f[0] = bf_lo(w.x); f[1] = bf_hi(w.x); f[2] = bf_lo(w.y); f[3] = bf_hi(w.y); f[4] = bf_lo(w.z); f[5] = bf_hi(w.z); f[6] = bf_lo(w.w); f[7] = bf_hi(w.w); }
; __device__ __forceinline__ void phase_norm(Frame& F, int l, int mode) {
;     ...
;         else {
; #pragma unroll
;             for (int q = 0; q < 4; ++q) unpack8(nb[q], v[q]); }
;         if (m + NGW < M) NORM_LOAD(m + NGW);
;     ...
;         float s = 0.f;
; #pragma unroll
;         for (int q = 0; q < 4; ++q)
; #pragma unroll
;             for (int j = 0; j < 8; ++j) s += v[q][j] * v[q][j];
;         const float rstd = __builtin_amdgcn_rsqf(wave_sum(s) * (1.f / D) + RMS_EPS);
; #pragma unroll
;         for (int q = 0; q < 4; ++q) { v[q][0] *= rstd * g[q][0].x; v[q][1] *= rstd * g[q][0].y; v[q][2] *= rstd * g[q][0].z; v[q][3] *= rstd * g[q][0].w; v[q][4] *= rstd * g[q][1].x; v[q][5] *= rstd * g[q][1].y; v[q][6] *= rstd * g[q][1].z; v[q][7] *= rstd * g[q][1].w; }
;         if (mode == 2) {
; #pragma unroll
;             for (int q = 0; q < 4; ++q) { GAS f32x4* o = (GAS f32x4*)(out_ + (size_t)m * D + q * 512 + lane * 8); o[0] = (f32x4){v[q][0], v[q][1], v[q][2], v[q][3]}; o[1] = (f32x4){v[q][4], v[q][5], v[q][6], v[q][7]}; }
;             continue; }
	v_pk_mul_f32 v[56:57], v[102:103], v[212:213] op_sel_hi:[1,0]
	v_pk_mul_f32 v[58:59], v[104:105], v[212:213] op_sel_hi:[1,0]
	v_pk_mul_f32 v[60:61], v[106:107], v[212:213] op_sel_hi:[1,0]
	v_pk_mul_f32 v[62:63], v[108:109], v[212:213] op_sel_hi:[1,0]
	v_pk_mul_f32 v[64:65], v[110:111], v[212:213] op_sel_hi:[1,0]
	v_pk_mul_f32 v[66:67], v[112:113], v[212:213] op_sel_hi:[1,0]
	v_pk_mul_f32 v[36:37], v[4:5], v[36:37]
	v_pk_mul_f32 v[38:39], v[6:7], v[38:39]
	v_pk_mul_f32 v[40:41], v[8:9], v[40:41]
	v_pk_mul_f32 v[42:43], v[10:11], v[42:43]
	v_pk_mul_f32 v[44:45], v[12:13], v[44:45]
	v_pk_mul_f32 v[46:47], v[14:15], v[46:47]
	v_pk_mul_f32 v[48:49], v[16:17], v[48:49]
	v_pk_mul_f32 v[50:51], v[18:19], v[50:51]
	v_pk_mul_f32 v[52:53], v[20:21], v[52:53]
	v_pk_mul_f32 v[54:55], v[22:23], v[54:55]
	v_pk_mul_f32 v[56:57], v[24:25], v[56:57]
	v_pk_mul_f32 v[58:59], v[26:27], v[58:59]
	v_pk_mul_f32 v[60:61], v[28:29], v[60:61]
	v_pk_mul_f32 v[62:63], v[30:31], v[62:63]
	v_pk_mul_f32 v[64:65], v[32:33], v[64:65]
	v_pk_mul_f32 v[66:67], v[34:35], v[66:67]
	global_store_dwordx4 v210, v[36:39], s[36:37] offset:0
	global_store_dwordx4 v210, v[40:43], s[36:37] offset:16
	global_store_dwordx4 v210, v[44:47], s[36:37] offset:2048
	global_store_dwordx4 v210, v[48:51], s[36:37] offset:2064
	global_store_dwordx4 v210, v[52:55], s[38:39] offset:0
	global_store_dwordx4 v210, v[56:59], s[38:39] offset:16
	global_store_dwordx4 v210, v[60:63], s[38:39] offset:2048
	global_store_dwordx4 v210, v[64:67], s[38:39] offset:2064
	s_add_u32 s36, s36, 0x1000000
	s_addc_u32 s37, s37, 0
	s_add_u32 s38, s38, 0x1000000
	s_addc_u32 s39, s39, 0
	s_waitcnt vmcnt(44)
	v_lshlrev_b32_e32 v4, 16, v114
	v_and_b32_e32 v5, 0xffff0000, v114
	v_lshlrev_b32_e32 v6, 16, v115
	v_and_b32_e32 v7, 0xffff0000, v115
	v_lshlrev_b32_e32 v8, 16, v116
	v_and_b32_e32 v9, 0xffff0000, v116
	v_lshlrev_b32_e32 v10, 16, v117
	v_and_b32_e32 v11, 0xffff0000, v117
	v_lshlrev_b32_e32 v12, 16, v118
	v_and_b32_e32 v13, 0xffff0000, v118
	v_lshlrev_b32_e32 v14, 16, v119
	v_and_b32_e32 v15, 0xffff0000, v119
	v_lshlrev_b32_e32 v16, 16, v120
	v_and_b32_e32 v17, 0xffff0000, v120
	v_lshlrev_b32_e32 v18, 16, v121
	v_and_b32_e32 v19, 0xffff0000, v121
	v_lshlrev_b32_e32 v20, 16, v122
	v_and_b32_e32 v21, 0xffff0000, v122
	v_lshlrev_b32_e32 v22, 16, v123
	v_and_b32_e32 v23, 0xffff0000, v123
	v_lshlrev_b32_e32 v24, 16, v124
	v_and_b32_e32 v25, 0xffff0000, v124
	v_lshlrev_b32_e32 v26, 16, v125
	v_and_b32_e32 v27, 0xffff0000, v125
	v_lshlrev_b32_e32 v28, 16, v126
	v_and_b32_e32 v29, 0xffff0000, v126
	v_lshlrev_b32_e32 v30, 16, v127
	v_and_b32_e32 v31, 0xffff0000, v127
	v_lshlrev_b32_e32 v32, 16, v128
	v_and_b32_e32 v33, 0xffff0000, v128
	v_lshlrev_b32_e32 v34, 16, v129
	v_and_b32_e32 v35, 0xffff0000, v129
	v_pk_mul_f32 v[218:219], v[4:5], v[4:5]
	v_pk_fma_f32 v[218:219], v[6:7], v[6:7], v[218:219]
	v_pk_fma_f32 v[218:219], v[8:9], v[8:9], v[218:219]
	v_pk_fma_f32 v[218:219], v[10:11], v[10:11], v[218:219]
	v_pk_fma_f32 v[218:219], v[12:13], v[12:13], v[218:219]
	v_pk_fma_f32 v[218:219], v[14:15], v[14:15], v[218:219]
	v_pk_fma_f32 v[218:219], v[16:17], v[16:17], v[218:219]
	v_pk_fma_f32 v[218:219], v[18:19], v[18:19], v[218:219]
	v_pk_fma_f32 v[218:219], v[20:21], v[20:21], v[218:219]
	v_pk_fma_f32 v[218:219], v[22:23], v[22:23], v[218:219]
	v_pk_fma_f32 v[218:219], v[24:25], v[24:25], v[218:219]
	v_pk_fma_f32 v[218:219], v[26:27], v[26:27], v[218:219]
	v_pk_fma_f32 v[218:219], v[28:29], v[28:29], v[218:219]
	v_pk_fma_f32 v[218:219], v[30:31], v[30:31], v[218:219]
	v_pk_fma_f32 v[218:219], v[32:33], v[32:33], v[218:219]
	v_pk_fma_f32 v[218:219], v[34:35], v[34:35], v[218:219]
	v_add_f32_e32 v211, v218, v219
	s_nop 1
	v_add_f32_dpp v211, v211, v211 quad_perm:[1,0,3,2] row_mask:0xf bank_mask:0xf bound_ctrl:1
	s_nop 1
	v_add_f32_dpp v211, v211, v211 quad_perm:[2,3,0,1] row_mask:0xf bank_mask:0xf bound_ctrl:1
	s_nop 1
	v_add_f32_dpp v211, v211, v211 row_half_mirror row_mask:0xf bank_mask:0xf bound_ctrl:1
	s_nop 1
	v_add_f32_dpp v211, v211, v211 row_mirror row_mask:0xf bank_mask:0xf bound_ctrl:1
	s_nop 1
	v_readlane_b32 s24, v211, 0
	v_readlane_b32 s25, v211, 16
	v_readlane_b32 s62, v211, 32
	v_readlane_b32 s63, v211, 48
	s_nop 1
	v_mov_b32_e32 v212, s25
	v_mov_b32_e32 v214, s63
	v_add_f32_e32 v212, s24, v212
	v_add_f32_e32 v214, s62, v214
	v_add_f32_e32 v212, v212, v214
	v_fmamk_f32 v212, v212, 0x3a000000, v216
	v_rsq_f32_e32 v212, v212
	s_nop 0
	v_pk_mul_f32 v[36:37], v[82:83], v[212:213] op_sel_hi:[1,0]
	v_pk_mul_f32 v[38:39], v[84:85], v[212:213] op_sel_hi:[1,0]
	v_pk_mul_f32 v[40:41], v[86:87], v[212:213] op_sel_hi:[1,0]
	v_pk_mul_f32 v[42:43], v[88:89], v[212:213] op_sel_hi:[1,0]
	v_pk_mul_f32 v[44:45], v[90:91], v[212:213] op_sel_hi:[1,0]
	v_pk_mul_f32 v[46:47], v[92:93], v[212:213] op_sel_hi:[1,0]
	v_pk_mul_f32 v[48:49], v[94:95], v[212:213] op_sel_hi:[1,0]
	v_pk_mul_f32 v[50:51], v[96:97], v[212:213] op_sel_hi:[1,0]
	v_pk_mul_f32 v[52:53], v[98:99], v[212:213] op_sel_hi:[1,0]
	v_pk_mul_f32 v[54:55], v[100:101], v[212:213] op_sel_hi:[1,0]
	v_pk_mul_f32 v[56:57], v[102:103], v[212:213] op_sel_hi:[1,0]
	v_pk_mul_f32 v[58:59], v[104:105], v[212:213] op_sel_hi:[1,0]
	v_pk_mul_f32 v[60:61], v[106:107], v[212:213] op_sel_hi:[1,0]
	v_pk_mul_f32 v[62:63], v[108:109], v[212:213] op_sel_hi:[1,0]
	v_pk_mul_f32 v[64:65], v[110:111], v[212:213] op_sel_hi:[1,0]
	v_pk_mul_f32 v[66:67], v[112:113], v[212:213] op_sel_hi:[1,0]
	v_pk_mul_f32 v[36:37], v[4:5], v[36:37]
	v_pk_mul_f32 v[38:39], v[6:7], v[38:39]
	v_pk_mul_f32 v[40:41], v[8:9], v[40:41]
	v_pk_mul_f32 v[42:43], v[10:11], v[42:43]
	v_pk_mul_f32 v[44:45], v[12:13], v[44:45]
	v_pk_mul_f32 v[46:47], v[14:15], v[46:47]
	v_pk_mul_f32 v[48:49], v[16:17], v[48:49]
	v_pk_mul_f32 v[50:51], v[18:19], v[50:51]
	v_pk_mul_f32 v[52:53], v[20:21], v[52:53]
	v_pk_mul_f32 v[54:55], v[22:23], v[54:55]
	v_pk_mul_f32 v[56:57], v[24:25], v[56:57]
	v_pk_mul_f32 v[58:59], v[26:27], v[58:59]
	v_pk_mul_f32 v[60:61], v[28:29], v[60:61]
	v_pk_mul_f32 v[62:63], v[30:31], v[62:63]
	v_pk_mul_f32 v[64:65], v[32:33], v[64:65]
	v_pk_mul_f32 v[66:67], v[34:35], v[66:67]
	global_store_dwordx4 v210, v[36:39], s[36:37] offset:0
	global_store_dwordx4 v210, v[40:43], s[36:37] offset:16
	global_store_dwordx4 v210, v[44:47], s[36:37] offset:2048
	global_store_dwordx4 v210, v[48:51], s[36:37] offset:2064
	global_store_dwordx4 v210, v[52:55], s[38:39] offset:0
	global_store_dwordx4 v210, v[56:59], s[38:39] offset:16
	global_store_dwordx4 v210, v[60:63], s[38:39] offset:2048
	global_store_dwordx4 v210, v[64:67], s[38:39] offset:2064
	s_add_u32 s36, s36, 0x1000000
	s_addc_u32 s37, s37, 0
	s_add_u32 s38, s38, 0x1000000
	s_addc_u32 s39, s39, 0
	s_waitcnt vmcnt(40)
; #define GAS __attribute__((address_space(1)))
; __device__ __forceinline__ void unpack8(const v4u w, float (&f)[8]) { f[0] = bf_lo(w.x); f[1] = bf_hi(w.x); f[2] = bf_lo(w.y); f[3] = bf_hi(w.y); f[4] = bf_lo(w.z); f[5] = bf_hi(w.z); f[6] = bf_lo(w.w); f[7] = bf_hi(w.w); }
; __device__ __forceinline__ void phase_norm(Frame& F, int l, int mode) {
;     ...
;         else {
; #pragma unroll
;             for (int q = 0; q < 4; ++q) unpack8(nb[q], v[q]); }
;         if (m + NGW < M) NORM_LOAD(m + NGW);
;     ...
;         float s = 0.f;
; #pragma unroll
;         for (int q = 0; q < 4; ++q)
; #pragma unroll
;             for (int j = 0; j < 8; ++j) s += v[q][j] * v[q][j];
;         const float rstd = __builtin_amdgcn_rsqf(wave_sum(s) * (1.f / D) + RMS_EPS);
; #pragma unroll
;         for (int q = 0; q < 4; ++q) { v[q][0] *= rstd * g[q][0].x; v[q][1] *= rstd * g[q][0].y; v[q][2] *= rstd * g[q][0].z; v[q][3] *= rstd * g[q][0].w; v[q][4] *= rstd * g[q][1].x; v[q][5] *= rstd * g[q][1].y; v[q][6] *= rstd * g[q][1].z; v[q][7] *= rstd * g[q][1].w; }
;         if (mode == 2) {
; #pragma unroll
;             for (int q = 0; q < 4; ++q) { GAS f32x4* o = (GAS f32x4*)(out_ + (size_t)m * D + q * 512 + lane * 8); o[0] = (f32x4){v[q][0], v[q][1], v[q][2], v[q][3]}; o[1] = (f32x4){v[q][4], v[q][5], v[q][6], v[q][7]}; }
;             continue; }
	v_lshlrev_b32_e32 v4, 16, v130
	v_and_b32_e32 v5, 0xffff0000, v130
	v_lshlrev_b32_e32 v6, 16, v131
	v_and_b32_e32 v7, 0xffff0000, v131
	v_lshlrev_b32_e32 v8, 16, v132
	v_and_b32_e32 v9, 0xffff0000, v132
	v_lshlrev_b32_e32 v10, 16, v133
	v_and_b32_e32 v11, 0xffff0000, v133
	v_lshlrev_b32_e32 v12, 16, v134
	v_and_b32_e32 v13, 0xffff0000, v134
	v_lshlrev_b32_e32 v14, 16, v135
	v_and_b32_e32 v15, 0xffff0000, v135
	v_lshlrev_b32_e32 v16, 16, v136
	v_and_b32_e32 v17, 0xffff0000, v136
	v_lshlrev_b32_e32 v18, 16, v137
	v_and_b32_e32 v19, 0xffff0000, v137
	v_lshlrev_b32_e32 v20, 16, v138
	v_and_b32_e32 v21, 0xffff0000, v138
	v_lshlrev_b32_e32 v22, 16, v139
	v_and_b32_e32 v23, 0xffff0000, v139
	v_lshlrev_b32_e32 v24, 16, v140
	v_and_b32_e32 v25, 0xffff0000, v140
	v_lshlrev_b32_e32 v26, 16, v141
	v_and_b32_e32 v27, 0xffff0000, v141
	v_lshlrev_b32_e32 v28, 16, v142
	v_and_b32_e32 v29, 0xffff0000, v142
	v_lshlrev_b32_e32 v30, 16, v143
	v_and_b32_e32 v31, 0xffff0000, v143
	v_lshlrev_b32_e32 v32, 16, v144
	v_and_b32_e32 v33, 0xffff0000, v144
	v_lshlrev_b32_e32 v34, 16, v145
	v_and_b32_e32 v35, 0xffff0000, v145
	v_pk_mul_f32 v[218:219], v[4:5], v[4:5]
	v_pk_fma_f32 v[218:219], v[6:7], v[6:7], v[218:219]
	v_pk_fma_f32 v[218:219], v[8:9], v[8:9], v[218:219]
	v_pk_fma_f32 v[218:219], v[10:11], v[10:11], v[218:219]
	v_pk_fma_f32 v[218:219], v[12:13], v[12:13], v[218:219]
	v_pk_fma_f32 v[218:219], v[14:15], v[14:15], v[218:219]
	v_pk_fma_f32 v[218:219], v[16:17], v[16:17], v[218:219]
	v_pk_fma_f32 v[218:219], v[18:19], v[18:19], v[218:219]
	v_pk_fma_f32 v[218:219], v[20:21], v[20:21], v[218:219]
	v_pk_fma_f32 v[218:219], v[22:23], v[22:23], v[218:219]
	v_pk_fma_f32 v[218:219], v[24:25], v[24:25], v[218:219]
	v_pk_fma_f32 v[218:219], v[26:27], v[26:27], v[218:219]
	v_pk_fma_f32 v[218:219], v[28:29], v[28:29], v[218:219]
	v_pk_fma_f32 v[218:219], v[30:31], v[30:31], v[218:219]
	v_pk_fma_f32 v[218:219], v[32:33], v[32:33], v[218:219]
	v_pk_fma_f32 v[218:219], v[34:35], v[34:35], v[218:219]
	v_add_f32_e32 v211, v218, v219
	s_nop 1
	v_add_f32_dpp v211, v211, v211 quad_perm:[1,0,3,2] row_mask:0xf bank_mask:0xf bound_ctrl:1
	s_nop 1
	v_add_f32_dpp v211, v211, v211 quad_perm:[2,3,0,1] row_mask:0xf bank_mask:0xf bound_ctrl:1
	s_nop 1
	v_add_f32_dpp v211, v211, v211 row_half_mirror row_mask:0xf bank_mask:0xf bound_ctrl:1
	s_nop 1
	v_add_f32_dpp v211, v211, v211 row_mirror row_mask:0xf bank_mask:0xf bound_ctrl:1
	s_nop 1
	v_readlane_b32 s24, v211, 0
	v_readlane_b32 s25, v211, 16
	v_readlane_b32 s62, v211, 32
	v_readlane_b32 s63, v211, 48
	s_nop 1
	v_mov_b32_e32 v212, s25
	v_mov_b32_e32 v214, s63
	v_add_f32_e32 v212, s24, v212
	v_add_f32_e32 v214, s62, v214
	v_add_f32_e32 v212, v212, v214
	v_fmamk_f32 v212, v212, 0x3a000000, v216
	v_rsq_f32_e32 v212, v212
	s_nop 0
	v_pk_mul_f32 v[36:37], v[82:83], v[212:213] op_sel_hi:[1,0]
	v_pk_mul_f32 v[38:39], v[84:85], v[212:213] op_sel_hi:[1,0]
	v_pk_mul_f32 v[40:41], v[86:87], v[212:213] op_sel_hi:[1,0]
	v_pk_mul_f32 v[42:43], v[88:89], v[212:213] op_sel_hi:[1,0]
	v_pk_mul_f32 v[44:45], v[90:91], v[212:213] op_sel_hi:[1,0]
	v_pk_mul_f32 v[46:47], v[92:93], v[212:213] op_sel_hi:[1,0]
	v_pk_mul_f32 v[48:49], v[94:95], v[212:213] op_sel_hi:[1,0]
	v_pk_mul_f32 v[50:51], v[96:97], v[212:213] op_sel_hi:[1,0]
	v_pk_mul_f32 v[52:53], v[98:99], v[212:213] op_sel_hi:[1,0]
	v_pk_mul_f32 v[54:55], v[100:101], v[212:213] op_sel_hi:[1,0]
	v_pk_mul_f32 v[56:57], v[102:103], v[212:213] op_sel_hi:[1,0]
	v_pk_mul_f32 v[58:59], v[104:105], v[212:213] op_sel_hi:[1,0]
	v_pk_mul_f32 v[60:61], v[106:107], v[212:213] op_sel_hi:[1,0]
	v_pk_mul_f32 v[62:63], v[108:109], v[212:213] op_sel_hi:[1,0]
	v_pk_mul_f32 v[64:65], v[110:111], v[212:213] op_sel_hi:[1,0]
	v_pk_mul_f32 v[66:67], v[112:113], v[212:213] op_sel_hi:[1,0]
	v_pk_mul_f32 v[36:37], v[4:5], v[36:37]
	v_pk_mul_f32 v[38:39], v[6:7], v[38:39]
	v_pk_mul_f32 v[40:41], v[8:9], v[40:41]
	v_pk_mul_f32 v[42:43], v[10:11], v[42:43]
	v_pk_mul_f32 v[44:45], v[12:13], v[44:45]
	v_pk_mul_f32 v[46:47], v[14:15], v[46:47]
	v_pk_mul_f32 v[48:49], v[16:17], v[48:49]
	v_pk_mul_f32 v[50:51], v[18:19], v[50:51]
	v_pk_mul_f32 v[52:53], v[20:21], v[52:53]
	v_pk_mul_f32 v[54:55], v[22:23], v[54:55]
	v_pk_mul_f32 v[56:57], v[24:25], v[56:57]
	v_pk_mul_f32 v[58:59], v[26:27], v[58:59]
	v_pk_mul_f32 v[60:61], v[28:29], v[60:61]
	v_pk_mul_f32 v[62:63], v[30:31], v[62:63]
	v_pk_mul_f32 v[64:65], v[32:33], v[64:65]
	v_pk_mul_f32 v[66:67], v[34:35], v[66:67]
	global_store_dwordx4 v210, v[36:39], s[36:37] offset:0
	global_store_dwordx4 v210, v[40:43], s[36:37] offset:16
	global_store_dwordx4 v210, v[44:47], s[36:37] offset:2048
	global_store_dwordx4 v210, v[48:51], s[36:37] offset:2064
	global_store_dwordx4 v210, v[52:55], s[38:39] offset:0
	global_store_dwordx4 v210, v[56:59], s[38:39] offset:16
	global_store_dwordx4 v210, v[60:63], s[38:39] offset:2048
	global_store_dwordx4 v210, v[64:67], s[38:39] offset:2064
	s_add_u32 s36, s36, 0x1000000
	s_addc_u32 s37, s37, 0
	s_add_u32 s38, s38, 0x1000000
	s_addc_u32 s39, s39, 0
	s_waitcnt vmcnt(36)
; #define GAS __attribute__((address_space(1)))
; __device__ __forceinline__ void unpack8(const v4u w, float (&f)[8]) { f[0] = bf_lo(w.x); f[1] = bf_hi(w.x); f[2] = bf_lo(w.y); f[3] = bf_hi(w.y); f[4] = bf_lo(w.z); f[5] = bf_hi(w.z); f[6] = bf_lo(w.w); f[7] = bf_hi(w.w); }
; __device__ __forceinline__ void phase_norm(Frame& F, int l, int mode) {
;     ...
;         else {
; #pragma unroll
;             for (int q = 0; q < 4; ++q) unpack8(nb[q], v[q]); }
;         if (m + NGW < M) NORM_LOAD(m + NGW);
;     ...
;         float s = 0.f;
; #pragma unroll
;         for (int q = 0; q < 4; ++q)
; #pragma unroll
;             for (int j = 0; j < 8; ++j) s += v[q][j] * v[q][j];
;         const float rstd = __builtin_amdgcn_rsqf(wave_sum(s) * (1.f / D) + RMS_EPS);
; #pragma unroll
;         for (int q = 0; q < 4; ++q) { v[q][0] *= rstd * g[q][0].x; v[q][1] *= rstd * g[q][0].y; v[q][2] *= rstd * g[q][0].z; v[q][3] *= rstd * g[q][0].w; v[q][4] *= rstd * g[q][1].x; v[q][5] *= rstd * g[q][1].y; v[q][6] *= rstd * g[q][1].z; v[q][7] *= rstd * g[q][1].w; }
;         if (mode == 2) {
; #pragma unroll
;             for (int q = 0; q < 4; ++q) { GAS f32x4* o = (GAS f32x4*)(out_ + (size_t)m * D + q * 512 + lane * 8); o[0] = (f32x4){v[q][0], v[q][1], v[q][2], v[q][3]}; o[1] = (f32x4){v[q][4], v[q][5], v[q][6], v[q][7]}; }
;             continue; }
	v_lshlrev_b32_e32 v4, 16, v146
	v_and_b32_e32 v5, 0xffff0000, v146
	v_lshlrev_b32_e32 v6, 16, v147
	v_and_b32_e32 v7, 0xffff0000, v147
	v_lshlrev_b32_e32 v8, 16, v148
	v_and_b32_e32 v9, 0xffff0000, v148
	v_lshlrev_b32_e32 v10, 16, v149
	v_and_b32_e32 v11, 0xffff0000, v149
	v_lshlrev_b32_e32 v12, 16, v150
	v_and_b32_e32 v13, 0xffff0000, v150
	v_lshlrev_b32_e32 v14, 16, v151
	v_and_b32_e32 v15, 0xffff0000, v151
	v_lshlrev_b32_e32 v16, 16, v152
	v_and_b32_e32 v17, 0xffff0000, v152
	v_lshlrev_b32_e32 v18, 16, v153
	v_and_b32_e32 v19, 0xffff0000, v153
	v_lshlrev_b32_e32 v20, 16, v154
	v_and_b32_e32 v21, 0xffff0000, v154
	v_lshlrev_b32_e32 v22, 16, v155
	v_and_b32_e32 v23, 0xffff0000, v155
	v_lshlrev_b32_e32 v24, 16, v156
	v_and_b32_e32 v25, 0xffff0000, v156
	v_lshlrev_b32_e32 v26, 16, v157
	v_and_b32_e32 v27, 0xffff0000, v157
	v_lshlrev_b32_e32 v28, 16, v158
	v_and_b32_e32 v29, 0xffff0000, v158
	v_lshlrev_b32_e32 v30, 16, v159
	v_and_b32_e32 v31, 0xffff0000, v159
	v_lshlrev_b32_e32 v32, 16, v160
	v_and_b32_e32 v33, 0xffff0000, v160
	v_lshlrev_b32_e32 v34, 16, v161
	v_and_b32_e32 v35, 0xffff0000, v161
	v_pk_mul_f32 v[218:219], v[4:5], v[4:5]
	v_pk_fma_f32 v[218:219], v[6:7], v[6:7], v[218:219]
	v_pk_fma_f32 v[218:219], v[8:9], v[8:9], v[218:219]
	v_pk_fma_f32 v[218:219], v[10:11], v[10:11], v[218:219]
	v_pk_fma_f32 v[218:219], v[12:13], v[12:13], v[218:219]
	v_pk_fma_f32 v[218:219], v[14:15], v[14:15], v[218:219]
	v_pk_fma_f32 v[218:219], v[16:17], v[16:17], v[218:219]
	v_pk_fma_f32 v[218:219], v[18:19], v[18:19], v[218:219]
	v_pk_fma_f32 v[218:219], v[20:21], v[20:21], v[218:219]
	v_pk_fma_f32 v[218:219], v[22:23], v[22:23], v[218:219]
	v_pk_fma_f32 v[218:219], v[24:25], v[24:25], v[218:219]
	v_pk_fma_f32 v[218:219], v[26:27], v[26:27], v[218:219]
	v_pk_fma_f32 v[218:219], v[28:29], v[28:29], v[218:219]
	v_pk_fma_f32 v[218:219], v[30:31], v[30:31], v[218:219]
	v_pk_fma_f32 v[218:219], v[32:33], v[32:33], v[218:219]
	v_pk_fma_f32 v[218:219], v[34:35], v[34:35], v[218:219]
	v_add_f32_e32 v211, v218, v219
	s_nop 1
	v_add_f32_dpp v211, v211, v211 quad_perm:[1,0,3,2] row_mask:0xf bank_mask:0xf bound_ctrl:1
	s_nop 1
	v_add_f32_dpp v211, v211, v211 quad_perm:[2,3,0,1] row_mask:0xf bank_mask:0xf bound_ctrl:1
	s_nop 1
	v_add_f32_dpp v211, v211, v211 row_half_mirror row_mask:0xf bank_mask:0xf bound_ctrl:1
	s_nop 1
	v_add_f32_dpp v211, v211, v211 row_mirror row_mask:0xf bank_mask:0xf bound_ctrl:1
	s_nop 1
	v_readlane_b32 s24, v211, 0
	v_readlane_b32 s25, v211, 16
	v_readlane_b32 s62, v211, 32
	v_readlane_b32 s63, v211, 48
	s_nop 1
	v_mov_b32_e32 v212, s25
	v_mov_b32_e32 v214, s63
	v_add_f32_e32 v212, s24, v212
	v_add_f32_e32 v214, s62, v214
	v_add_f32_e32 v212, v212, v214
	v_fmamk_f32 v212, v212, 0x3a000000, v216
	v_rsq_f32_e32 v212, v212
	s_nop 0
	v_pk_mul_f32 v[36:37], v[82:83], v[212:213] op_sel_hi:[1,0]
	v_pk_mul_f32 v[38:39], v[84:85], v[212:213] op_sel_hi:[1,0]
	v_pk_mul_f32 v[40:41], v[86:87], v[212:213] op_sel_hi:[1,0]
	v_pk_mul_f32 v[42:43], v[88:89], v[212:213] op_sel_hi:[1,0]
	v_pk_mul_f32 v[44:45], v[90:91], v[212:213] op_sel_hi:[1,0]
	v_pk_mul_f32 v[46:47], v[92:93], v[212:213] op_sel_hi:[1,0]
	v_pk_mul_f32 v[48:49], v[94:95], v[212:213] op_sel_hi:[1,0]
	v_pk_mul_f32 v[50:51], v[96:97], v[212:213] op_sel_hi:[1,0]
	v_pk_mul_f32 v[52:53], v[98:99], v[212:213] op_sel_hi:[1,0]
	v_pk_mul_f32 v[54:55], v[100:101], v[212:213] op_sel_hi:[1,0]
	v_pk_mul_f32 v[56:57], v[102:103], v[212:213] op_sel_hi:[1,0]
	v_pk_mul_f32 v[58:59], v[104:105], v[212:213] op_sel_hi:[1,0]
	v_pk_mul_f32 v[60:61], v[106:107], v[212:213] op_sel_hi:[1,0]
	v_pk_mul_f32 v[62:63], v[108:109], v[212:213] op_sel_hi:[1,0]
	v_pk_mul_f32 v[64:65], v[110:111], v[212:213] op_sel_hi:[1,0]
	v_pk_mul_f32 v[66:67], v[112:113], v[212:213] op_sel_hi:[1,0]
	v_pk_mul_f32 v[36:37], v[4:5], v[36:37]
	v_pk_mul_f32 v[38:39], v[6:7], v[38:39]
	v_pk_mul_f32 v[40:41], v[8:9], v[40:41]
	v_pk_mul_f32 v[42:43], v[10:11], v[42:43]
	v_pk_mul_f32 v[44:45], v[12:13], v[44:45]
	v_pk_mul_f32 v[46:47], v[14:15], v[46:47]
	v_pk_mul_f32 v[48:49], v[16:17], v[48:49]
	v_pk_mul_f32 v[50:51], v[18:19], v[50:51]
	v_pk_mul_f32 v[52:53], v[20:21], v[52:53]
	v_pk_mul_f32 v[54:55], v[22:23], v[54:55]
	v_pk_mul_f32 v[56:57], v[24:25], v[56:57]
	v_pk_mul_f32 v[58:59], v[26:27], v[58:59]
	v_pk_mul_f32 v[60:61], v[28:29], v[60:61]
	v_pk_mul_f32 v[62:63], v[30:31], v[62:63]
	v_pk_mul_f32 v[64:65], v[32:33], v[64:65]
	v_pk_mul_f32 v[66:67], v[34:35], v[66:67]
	global_store_dwordx4 v210, v[36:39], s[36:37] offset:0
	global_store_dwordx4 v210, v[40:43], s[36:37] offset:16
	global_store_dwordx4 v210, v[44:47], s[36:37] offset:2048
	global_store_dwordx4 v210, v[48:51], s[36:37] offset:2064
	global_store_dwordx4 v210, v[52:55], s[38:39] offset:0
	global_store_dwordx4 v210, v[56:59], s[38:39] offset:16
	global_store_dwordx4 v210, v[60:63], s[38:39] offset:2048
	global_store_dwordx4 v210, v[64:67], s[38:39] offset:2064
	s_add_u32 s36, s36, 0x1000000
	s_addc_u32 s37, s37, 0
	s_add_u32 s38, s38, 0x1000000
	s_addc_u32 s39, s39, 0
	s_waitcnt vmcnt(32)
; #define GAS __attribute__((address_space(1)))
; __device__ __forceinline__ void phase_norm(Frame& F, int l, int mode) {
;     ...
;         float s = 0.f;
; #pragma unroll
;         for (int q = 0; q < 4; ++q)
; #pragma unroll
;             for (int j = 0; j < 8; ++j) s += v[q][j] * v[q][j];
;         const float rstd = __builtin_amdgcn_rsqf(wave_sum(s) * (1.f / D) + RMS_EPS);
; #pragma unroll
;         for (int q = 0; q < 4; ++q) { v[q][0] *= rstd * g[q][0].x; v[q][1] *= rstd * g[q][0].y; v[q][2] *= rstd * g[q][0].z; v[q][3] *= rstd * g[q][0].w; v[q][4] *= rstd * g[q][1].x; v[q][5] *= rstd * g[q][1].y; v[q][6] *= rstd * g[q][1].z; v[q][7] *= rstd * g[q][1].w; }
;         if (mode == 2) {
; #pragma unroll
;             for (int q = 0; q < 4; ++q) { GAS f32x4* o = (GAS f32x4*)(out_ + (size_t)m * D + q * 512 + lane * 8); o[0] = (f32x4){v[q][0], v[q][1], v[q][2], v[q][3]}; o[1] = (f32x4){v[q][4], v[q][5], v[q][6], v[q][7]}; }
;             continue; }
	v_lshlrev_b32_e32 v4, 16, v162
	v_and_b32_e32 v5, 0xffff0000, v162
	v_lshlrev_b32_e32 v6, 16, v163
	v_and_b32_e32 v7, 0xffff0000, v163
	v_lshlrev_b32_e32 v8, 16, v164
	v_and_b32_e32 v9, 0xffff0000, v164
	v_lshlrev_b32_e32 v10, 16, v165
	v_and_b32_e32 v11, 0xffff0000, v165
	v_lshlrev_b32_e32 v12, 16, v166
	v_and_b32_e32 v13, 0xffff0000, v166
	v_lshlrev_b32_e32 v14, 16, v167
	v_and_b32_e32 v15, 0xffff0000, v167
	v_lshlrev_b32_e32 v16, 16, v168
	v_and_b32_e32 v17, 0xffff0000, v168
	v_lshlrev_b32_e32 v18, 16, v169
	v_and_b32_e32 v19, 0xffff0000, v169
	v_lshlrev_b32_e32 v20, 16, v170
	v_and_b32_e32 v21, 0xffff0000, v170
	v_lshlrev_b32_e32 v22, 16, v171
	v_and_b32_e32 v23, 0xffff0000, v171
	v_lshlrev_b32_e32 v24, 16, v172
	v_and_b32_e32 v25, 0xffff0000, v172
	v_lshlrev_b32_e32 v26, 16, v173
	v_and_b32_e32 v27, 0xffff0000, v173
	v_lshlrev_b32_e32 v28, 16, v174
	v_and_b32_e32 v29, 0xffff0000, v174
	v_lshlrev_b32_e32 v30, 16, v175
	v_and_b32_e32 v31, 0xffff0000, v175
	v_lshlrev_b32_e32 v32, 16, v176
	v_and_b32_e32 v33, 0xffff0000, v176
	v_lshlrev_b32_e32 v34, 16, v177
	v_and_b32_e32 v35, 0xffff0000, v177
	v_pk_mul_f32 v[218:219], v[4:5], v[4:5]
	v_pk_fma_f32 v[218:219], v[6:7], v[6:7], v[218:219]
	v_pk_fma_f32 v[218:219], v[8:9], v[8:9], v[218:219]
	v_pk_fma_f32 v[218:219], v[10:11], v[10:11], v[218:219]
	v_pk_fma_f32 v[218:219], v[12:13], v[12:13], v[218:219]
	v_pk_fma_f32 v[218:219], v[14:15], v[14:15], v[218:219]
	v_pk_fma_f32 v[218:219], v[16:17], v[16:17], v[218:219]
	v_pk_fma_f32 v[218:219], v[18:19], v[18:19], v[218:219]
	v_pk_fma_f32 v[218:219], v[20:21], v[20:21], v[218:219]
	v_pk_fma_f32 v[218:219], v[22:23], v[22:23], v[218:219]
	v_pk_fma_f32 v[218:219], v[24:25], v[24:25], v[218:219]
	v_pk_fma_f32 v[218:219], v[26:27], v[26:27], v[218:219]
	v_pk_fma_f32 v[218:219], v[28:29], v[28:29], v[218:219]
	v_pk_fma_f32 v[218:219], v[30:31], v[30:31], v[218:219]
	v_pk_fma_f32 v[218:219], v[32:33], v[32:33], v[218:219]
	v_pk_fma_f32 v[218:219], v[34:35], v[34:35], v[218:219]
	v_add_f32_e32 v211, v218, v219
	s_nop 1
	v_add_f32_dpp v211, v211, v211 quad_perm:[1,0,3,2] row_mask:0xf bank_mask:0xf bound_ctrl:1
	s_nop 1
	v_add_f32_dpp v211, v211, v211 quad_perm:[2,3,0,1] row_mask:0xf bank_mask:0xf bound_ctrl:1
	s_nop 1
	v_add_f32_dpp v211, v211, v211 row_half_mirror row_mask:0xf bank_mask:0xf bound_ctrl:1
	s_nop 1
	v_add_f32_dpp v211, v211, v211 row_mirror row_mask:0xf bank_mask:0xf bound_ctrl:1
	s_nop 1
	v_readlane_b32 s24, v211, 0
	v_readlane_b32 s25, v211, 16
	v_readlane_b32 s62, v211, 32
	v_readlane_b32 s63, v211, 48
	s_nop 1
	v_mov_b32_e32 v212, s25
	v_mov_b32_e32 v214, s63
	v_add_f32_e32 v212, s24, v212
	v_add_f32_e32 v214, s62, v214
	v_add_f32_e32 v212, v212, v214
	v_fmamk_f32 v212, v212, 0x3a000000, v216
	v_rsq_f32_e32 v212, v212
	s_nop 0
	v_pk_mul_f32 v[36:37], v[82:83], v[212:213] op_sel_hi:[1,0]
	v_pk_mul_f32 v[38:39], v[84:85], v[212:213] op_sel_hi:[1,0]
	v_pk_mul_f32 v[40:41], v[86:87], v[212:213] op_sel_hi:[1,0]
	v_pk_mul_f32 v[42:43], v[88:89], v[212:213] op_sel_hi:[1,0]
	v_pk_mul_f32 v[44:45], v[90:91], v[212:213] op_sel_hi:[1,0]
	v_pk_mul_f32 v[46:47], v[92:93], v[212:213] op_sel_hi:[1,0]
	v_pk_mul_f32 v[48:49], v[94:95], v[212:213] op_sel_hi:[1,0]
	v_pk_mul_f32 v[50:51], v[96:97], v[212:213] op_sel_hi:[1,0]
	v_pk_mul_f32 v[52:53], v[98:99], v[212:213] op_sel_hi:[1,0]
	v_pk_mul_f32 v[54:55], v[100:101], v[212:213] op_sel_hi:[1,0]
	v_pk_mul_f32 v[56:57], v[102:103], v[212:213] op_sel_hi:[1,0]
	v_pk_mul_f32 v[58:59], v[104:105], v[212:213] op_sel_hi:[1,0]
	v_pk_mul_f32 v[60:61], v[106:107], v[212:213] op_sel_hi:[1,0]
	v_pk_mul_f32 v[62:63], v[108:109], v[212:213] op_sel_hi:[1,0]
	v_pk_mul_f32 v[64:65], v[110:111], v[212:213] op_sel_hi:[1,0]
	v_pk_mul_f32 v[66:67], v[112:113], v[212:213] op_sel_hi:[1,0]
	v_pk_mul_f32 v[36:37], v[4:5], v[36:37]
	v_pk_mul_f32 v[38:39], v[6:7], v[38:39]
	v_pk_mul_f32 v[40:41], v[8:9], v[40:41]
	v_pk_mul_f32 v[42:43], v[10:11], v[42:43]
	v_pk_mul_f32 v[44:45], v[12:13], v[44:45]
	v_pk_mul_f32 v[46:47], v[14:15], v[46:47]
	v_pk_mul_f32 v[48:49], v[16:17], v[48:49]
	v_pk_mul_f32 v[50:51], v[18:19], v[50:51]
	v_pk_mul_f32 v[52:53], v[20:21], v[52:53]
	v_pk_mul_f32 v[54:55], v[22:23], v[54:55]
	v_pk_mul_f32 v[56:57], v[24:25], v[56:57]
	v_pk_mul_f32 v[58:59], v[26:27], v[58:59]
	v_pk_mul_f32 v[60:61], v[28:29], v[60:61]
	v_pk_mul_f32 v[62:63], v[30:31], v[62:63]
	v_pk_mul_f32 v[64:65], v[32:33], v[64:65]
	v_pk_mul_f32 v[66:67], v[34:35], v[66:67]
	global_store_dwordx4 v210, v[36:39], s[36:37] offset:0
	global_store_dwordx4 v210, v[40:43], s[36:37] offset:16
	global_store_dwordx4 v210, v[44:47], s[36:37] offset:2048
	global_store_dwordx4 v210, v[48:51], s[36:37] offset:2064
	global_store_dwordx4 v210, v[52:55], s[38:39] offset:0
	global_store_dwordx4 v210, v[56:59], s[38:39] offset:16
	global_store_dwordx4 v210, v[60:63], s[38:39] offset:2048
	global_store_dwordx4 v210, v[64:67], s[38:39] offset:2064
	s_add_u32 s36, s36, 0x1000000
	s_addc_u32 s37, s37, 0
	s_add_u32 s38, s38, 0x1000000
	s_addc_u32 s39, s39, 0
	s_add_i32 s16, s16, 0x4000
; #define GAS __attribute__((address_space(1)))
; __device__ __forceinline__ void unpack8(const v4u w, float (&f)[8]) { f[0] = bf_lo(w.x); f[1] = bf_hi(w.x); f[2] = bf_lo(w.y); f[3] = bf_hi(w.y); f[4] = bf_lo(w.z); f[5] = bf_hi(w.z); f[6] = bf_lo(w.w); f[7] = bf_hi(w.w); }
; __device__ __forceinline__ v4u pack8(const float (&f)[8]) { v4u o; o.x = pk2(f[0], f[1]); o.y = pk2(f[2], f[3]); o.z = pk2(f[4], f[5]); o.w = pk2(f[6], f[7]); return o; }
; __device__ __forceinline__ void phase_norm(Frame& F, int l, int mode) {
;     ...
;     for (int m = gw; m < M; m += NGW) {
;         float v[4][8];
;         if (from_in) {
; #pragma unroll
;             for (int q = 0; q < 4; ++q) { v[q][0] = nf[q][0].x; v[q][1] = nf[q][0].y; v[q][2] = nf[q][0].z; v[q][3] = nf[q][0].w; v[q][4] = nf[q][1].x; v[q][5] = nf[q][1].y; v[q][6] = nf[q][1].z; v[q][7] = nf[q][1].w; } }
;         else {
; #pragma unroll
;             for (int q = 0; q < 4; ++q) unpack8(nb[q], v[q]); }
;         if (m + NGW < M) NORM_LOAD(m + NGW);
;         const bool slab = (m >= MP) && !from_in;
;         if (slab) { const GAS bf16* SL = (const GAS bf16*)(ws_ + WS_WD) + (size_t)(m - MP) * D;
; #pragma unroll
;             for (int hq = 0; hq < 2; ++hq) {
;                 v4u sv[2][8];
; #pragma unroll
;                 for (int q = 0; q < 2; ++q)
; #pragma unroll
;                     for (int k8 = 0; k8 < 8; ++k8) sv[q][k8] = *(const GAS v4u*)(SL + (size_t)k8 * MS * D + (2 * hq + q) * 512 + lane * 8);
; #pragma unroll
;                 for (int q = 0; q < 2; ++q)
; #pragma unroll
;                     for (int k8 = 0; k8 < 8; ++k8) { float p[8]; unpack8(sv[q][k8], p);
; #pragma unroll
;                         for (int j = 0; j < 8; ++j) v[2 * hq + q][j] += p[j]; } } }
;         if (from_in || (slab && mode != 2)) {
; #pragma unroll
;             for (int q = 0; q < 4; ++q) { const v4u w = pack8(v[q]); *(GAS v4u*)(XW + (size_t)m * D + q * 512 + lane * 8) = w; unpack8(w, v[q]); } }
.Lnf_final_done:
	s_cmpk_gt_i32 s16, 0x43ff
	s_cbranch_scc1 .LBB0_1298
	v_readlane_b32 s2, v254, 0
	v_readlane_b32 s3, v254, 1
	s_add_u32 s4, s14, 0x3d5a0000
	s_load_dwordx2 s[2:3], s[2:3], 0xc8
	s_waitcnt lgkmcnt(0)
	s_addc_u32 s11, s15, 0
	s_ashr_i32 s17, s16, 31
	s_lshl_b64 s[0:1], s[16:17], 12
	v_lshlrev_b32_e32 v0, 3, v0
	s_add_u32 s0, s4, s0
	v_ashrrev_i32_e32 v1, 31, v0
	s_addc_u32 s1, s11, s1
	v_lshlrev_b64 v[32:33], 1, v[0:1]
	v_lshlrev_b64 v[36:37], 2, v[0:1]
	v_lshl_add_u64 v[34:35], s[0:1], 0, v[32:33]
	v_lshl_add_u64 v[38:39], s[2:3], 0, v[36:37]
	s_mov_b64 s[0:1], 0x1800
	s_movk_i32 s10, 0x1000
	v_lshl_add_u64 v[40:41], v[38:39], 0, s[0:1]
	v_add_co_u32_e32 v42, vcc, s10, v38
	s_mov_b64 s[2:3], 0x1000
	s_nop 0
	v_addc_co_u32_e32 v43, vcc, 0, v39, vcc
	v_lshl_add_u64 v[44:45], v[38:39], 0, s[2:3]
	global_load_dwordx4 v[0:3], v[40:41], off offset:16
	global_load_dwordx4 v[4:7], v[42:43], off
	global_load_dwordx4 v[8:11], v[38:39], off offset:2064
	global_load_dwordx4 v[12:15], v[38:39], off offset:2048
	global_load_dwordx4 v[16:19], v[38:39], off offset:16
	global_load_dwordx4 v[20:23], v[38:39], off
	global_load_dwordx4 v[52:55], v[34:35], off offset:2048
	global_load_dwordx4 v[48:51], v[34:35], off offset:3072
	global_load_dwordx4 v[60:63], v[34:35], off
	global_load_dwordx4 v[56:59], v[34:35], off offset:1024
	global_load_dwordx4 v[24:27], v[42:43], off offset:2048
	global_load_dwordx4 v[28:31], v[44:45], off offset:16
	s_mov_b64 s[6:7], 0x43ba0000
	v_lshl_add_u64 v[34:35], s[14:15], 0, v[32:33]
	v_lshl_add_u64 v[80:81], v[34:35], 0, s[6:7]
	s_lshl_b64 s[6:7], s[16:17], 13
	s_add_u32 s12, s12, s6
	s_addc_u32 s13, s13, s7
	s_add_i32 s14, s16, s44
	s_ashr_i32 s15, s14, 31
	s_lshl_b64 s[6:7], s[44:45], 13
	v_lshl_add_u64 v[82:83], s[12:13], 0, v[36:37]
	s_lshl_b64 s[12:13], s[14:15], 12
	s_add_u32 s12, s4, s12
	s_addc_u32 s13, s11, s13
	s_mov_b64 s[8:9], 0x800
	v_lshl_add_u64 v[32:33], s[12:13], 0, v[32:33]
	v_lshl_add_u64 v[84:85], v[32:33], 0, s[8:9]
	s_mov_b32 s5, 0
	v_mov_b32_e32 v134, 0x358637bd
	s_waitcnt vmcnt(0)
	v_mov_b64_e32 v[36:37], v[52:53]
	v_mov_b64_e32 v[32:33], v[48:49]
	v_mov_b64_e32 v[44:45], v[60:61]
	v_mov_b64_e32 v[40:41], v[56:57]
	v_mov_b64_e32 v[34:35], v[50:51]
	v_mov_b64_e32 v[38:39], v[54:55]
	v_mov_b64_e32 v[42:43], v[58:59]
	v_mov_b64_e32 v[46:47], v[62:63]
	s_branch .LBB0_1294
